# GLA chain: barrier-1 vmcnt(0) removed (counted vmcnt(8) at loop end); EpiYa epilogue hand-scheduled (all gate loads up front); split-K tail fragment loads hoisted; gla_qk_item cumsum loop 4-token inte
# speedup vs baseline: 1.0061x; 1.0061x over previous
; #define MFMA16(a, b, c) __builtin_amdgcn_mfma_f32_16x16x32_bf16((a), (b), (c), 0, 0, 0)
; template <int MT, int NT, class Epi>
; __device__ __forceinline__ void tail_splitk(LAS unsigned char* lds, const bf16_t* A, const bf16_t* Bt, int K, int row_base, int n_rt, int col_base, int n_ct, int it0, const Epi& E) {
;     ...
;         const bf16_t* ap = A + (size_t)(r0 + fr) * K + fq * 8 + w * nks * 32; const bf16_t* bp = Bt + (size_t)(c0 + fr) * K + fq * 8 + w * nks * 32;
; #pragma unroll 4
;         for (int ks = 0; ks < nks; ++ks) {
;             bf16x8 af[MT], bfv[NT];
; #pragma unroll
;             for (int mt = 0; mt < MT; ++mt) af[mt] = *(const bf16x8*)(ap + (size_t)mt * 16 * K + ks * 32);
; #pragma unroll
;             for (int nt = 0; nt < NT; ++nt) bfv[nt] = *(const bf16x8*)(bp + (size_t)nt * 16 * K + ks * 32);
; #pragma unroll
;             for (int mt = 0; mt < MT; ++mt)
; #pragma unroll
;                 for (int nt = 0; nt < NT; ++nt) acc[mt][nt] = MFMA16(bfv[nt], af[mt], acc[mt][nt]);
;         }
.LBB0_142:
	s_ashr_i32 s0, s35, 31
	s_lshr_b32 s0, s0, 30
	s_add_i32 s0, s35, s0
	s_and_b32 s1, s0, 0x3fffffc
	s_sub_i32 s1, s35, s1
	s_lshl_b32 s40, s1, 6
	s_addk_i32 s40, 0x4000
	v_or_b32_e32 v0, s40, v7
	s_lshl_b32 s38, s0, 4
	v_lshlrev_b64 v[16:17], 11, v[0:1]
	s_andn2_b32 s38, s38, 63
	v_lshl_add_u64 v[114:115], v[2:3], 0, v[16:17]
	v_or_b32_e32 v12, s38, v7
	v_add_co_u32_e64 v116, s[0:1], s64, v114
	v_ashrrev_i32_e32 v13, 31, v12
	s_nop 0
	v_addc_co_u32_e64 v117, s[0:1], 0, v115, s[0:1]
	v_lshlrev_b64 v[12:13], 11, v[12:13]
	v_add_co_u32_e64 v120, s[0:1], s33, v114
	v_lshl_add_u64 v[112:113], v[4:5], 0, v[12:13]
	s_nop 0
	v_addc_co_u32_e64 v121, s[0:1], 0, v115, s[0:1]
	v_add_co_u32_e64 v118, s[0:1], s64, v112
	s_waitcnt lgkmcnt(0)
	global_load_dwordx4 v[148:151], v[112:113], off
	global_load_dwordx4 v[152:155], v[114:115], off
	v_addc_co_u32_e64 v119, s[0:1], 0, v113, s[0:1]
	v_add_co_u32_e64 v122, s[0:1], s33, v112
	global_load_dwordx4 v[164:167], v[116:117], off
	global_load_dwordx4 v[168:171], v[120:121], off
	v_addc_co_u32_e64 v123, s[0:1], 0, v113, s[0:1]
	v_add_co_u32_e64 v128, s[0:1], s6, v114
	s_nop 0
	s_nop 0
	v_addc_co_u32_e64 v129, s[0:1], 0, v115, s[0:1]
	v_add_co_u32_e64 v124, s[0:1], s6, v112
	global_load_dwordx4 v[172:175], v[118:119], off
	global_load_dwordx4 v[176:179], v[128:129], off
	global_load_dwordx4 v[180:183], v[112:113], off offset:64
	global_load_dwordx4 v[184:187], v[114:115], off offset:64
	v_addc_co_u32_e64 v125, s[0:1], 0, v113, s[0:1]
	global_load_dwordx4 v[204:207], v[122:123], off
	global_load_dwordx4 v[208:211], v[116:117], off offset:64
	global_load_dwordx4 v[212:215], v[120:121], off offset:64
	global_load_dwordx4 v[216:219], v[124:125], off
	global_load_dwordx4 v[220:223], v[128:129], off offset:64
	global_load_dwordx4 v[224:227], v[122:123], off offset:64
	global_load_dwordx4 v[228:231], v[124:125], off offset:64
	global_load_dwordx4 v[232:235], v[118:119], off offset:64
	s_nop 0
	s_nop 0
	s_nop 0
	s_nop 2
	global_load_dwordx4 v[236:239], v[112:113], off offset:128
	s_nop 0
	s_nop 0
	s_nop 0
	s_waitcnt vmcnt(0)
	s_nop 0
	s_nop 0
	s_nop 0
	v_mfma_f32_16x16x32_bf16 v[44:47], v[148:151], v[152:155], 0
	s_nop 0
	s_nop 0
	s_nop 0
	v_mfma_f32_16x16x32_bf16 v[56:59], v[148:151], v[164:167], 0
	v_mfma_f32_16x16x32_bf16 v[64:67], v[148:151], v[168:171], 0
	s_nop 0
	v_mfma_f32_16x16x32_bf16 v[12:15], v[148:151], v[176:179], 0
	v_mfma_f32_16x16x32_bf16 v[88:91], v[204:207], v[152:155], 0
	v_mfma_f32_16x16x32_bf16 v[100:103], v[204:207], v[164:167], 0
	v_mfma_f32_16x16x32_bf16 v[108:111], v[204:207], v[168:171], 0
	v_mfma_f32_16x16x32_bf16 v[48:51], v[204:207], v[176:179], 0
	v_mfma_f32_16x16x32_bf16 v[44:47], v[180:183], v[184:187], v[44:47]
	v_mfma_f32_16x16x32_bf16 v[56:59], v[180:183], v[208:211], v[56:59]
	v_mfma_f32_16x16x32_bf16 v[64:67], v[180:183], v[212:215], v[64:67]
	v_mfma_f32_16x16x32_bf16 v[12:15], v[180:183], v[220:223], v[12:15]
	v_mfma_f32_16x16x32_bf16 v[36:39], v[224:227], v[220:223], v[48:51]
	s_nop 2
	s_nop 0
	v_mfma_f32_16x16x32_bf16 v[80:83], v[172:175], v[152:155], 0
	v_mfma_f32_16x16x32_bf16 v[16:19], v[216:219], v[152:155], 0
	v_mfma_f32_16x16x32_bf16 v[96:99], v[172:175], v[164:167], 0
	v_mfma_f32_16x16x32_bf16 v[20:23], v[216:219], v[164:167], 0
	v_mfma_f32_16x16x32_bf16 v[104:107], v[172:175], v[168:171], 0
	v_mfma_f32_16x16x32_bf16 v[24:27], v[216:219], v[168:171], 0
	v_mfma_f32_16x16x32_bf16 v[28:31], v[172:175], v[176:179], 0
	v_mfma_f32_16x16x32_bf16 v[32:35], v[216:219], v[176:179], 0
	v_mfma_f32_16x16x32_bf16 v[68:71], v[232:235], v[184:187], v[80:83]
	v_mfma_f32_16x16x32_bf16 v[80:83], v[224:227], v[184:187], v[88:91]
	v_mfma_f32_16x16x32_bf16 v[16:19], v[228:231], v[184:187], v[16:19]
	v_mfma_f32_16x16x32_bf16 v[40:43], v[232:235], v[208:211], v[96:99]
	v_mfma_f32_16x16x32_bf16 v[88:91], v[224:227], v[208:211], v[100:103]
	v_mfma_f32_16x16x32_bf16 v[20:23], v[228:231], v[208:211], v[20:23]
	v_mfma_f32_16x16x32_bf16 v[52:55], v[232:235], v[212:215], v[104:107]
	v_mfma_f32_16x16x32_bf16 v[96:99], v[224:227], v[212:215], v[108:111]
	v_mfma_f32_16x16x32_bf16 v[24:27], v[228:231], v[212:215], v[24:27]
	v_mfma_f32_16x16x32_bf16 v[28:31], v[232:235], v[220:223], v[28:31]
	v_mfma_f32_16x16x32_bf16 v[32:35], v[228:231], v[220:223], v[32:35]
	global_load_dwordx4 v[148:151], v[114:115], off offset:128
	global_load_dwordx4 v[204:207], v[112:113], off offset:192
	global_load_dwordx4 v[180:183], v[114:115], off offset:192
	global_load_dwordx4 v[152:155], v[118:119], off offset:128
	global_load_dwordx4 v[164:167], v[118:119], off offset:192
	global_load_dwordx4 v[168:171], v[122:123], off offset:128
	global_load_dwordx4 v[172:175], v[122:123], off offset:192
	global_load_dwordx4 v[176:179], v[124:125], off offset:128
	global_load_dwordx4 v[216:219], v[124:125], off offset:192
	s_nop 0
	s_nop 0
	s_nop 0
	global_load_dwordx4 v[184:187], v[116:117], off offset:128
	s_nop 0
	global_load_dwordx4 v[208:211], v[116:117], off offset:192
	s_nop 0
	s_nop 0
	s_nop 0
	global_load_dwordx4 v[212:215], v[120:121], off offset:128
	s_nop 0
	s_waitcnt vmcnt(0)
; #define LAS __attribute__((address_space(3)))
; #define MFMA16(a, b, c) __builtin_amdgcn_mfma_f32_16x16x32_bf16((a), (b), (c), 0, 0, 0)
; template <int MT, int NT, class Epi>
; __device__ __forceinline__ void tail_splitk(LAS unsigned char* lds, const bf16_t* A, const bf16_t* Bt, int K, int row_base, int n_rt, int col_base, int n_ct, int it0, const Epi& E) {
;     ...
;         for (int ks = 0; ks < nks; ++ks) {
;             bf16x8 af[MT], bfv[NT];
; #pragma unroll
;             for (int mt = 0; mt < MT; ++mt) af[mt] = *(const bf16x8*)(ap + (size_t)mt * 16 * K + ks * 32);
; #pragma unroll
;             for (int nt = 0; nt < NT; ++nt) bfv[nt] = *(const bf16x8*)(bp + (size_t)nt * 16 * K + ks * 32);
; #pragma unroll
;             for (int mt = 0; mt < MT; ++mt)
; #pragma unroll
;                 for (int nt = 0; nt < NT; ++nt) acc[mt][nt] = MFMA16(bfv[nt], af[mt], acc[mt][nt]);
;         }
;         LAS float* pw = (LAS float*)(lds + w * WB);
; #pragma unroll
;         for (int mt = 0; mt < MT; ++mt)
; #pragma unroll
;             for (int nt = 0; nt < NT; ++nt) *(LAS f32x4*)(pw + (16 * mt + fr) * RS + 16 * nt + 4 * fq) = acc[mt][nt];
;         __syncthreads();
	s_nop 0
	s_nop 0
	s_nop 0
	v_mfma_f32_16x16x32_bf16 v[44:47], v[236:239], v[148:151], v[44:47]
	v_mfma_f32_16x16x32_bf16 v[68:71], v[152:155], v[148:151], v[68:71]
	v_mfma_f32_16x16x32_bf16 v[80:83], v[168:171], v[148:151], v[80:83]
	v_mfma_f32_16x16x32_bf16 v[16:19], v[176:179], v[148:151], v[16:19]
	s_nop 0
	s_nop 0
	s_nop 0
	v_mfma_f32_16x16x32_bf16 v[56:59], v[236:239], v[184:187], v[56:59]
	v_mfma_f32_16x16x32_bf16 v[40:43], v[152:155], v[184:187], v[40:43]
	v_mfma_f32_16x16x32_bf16 v[88:91], v[168:171], v[184:187], v[88:91]
	v_mfma_f32_16x16x32_bf16 v[20:23], v[176:179], v[184:187], v[20:23]
	s_nop 0
	s_nop 0
	global_load_dwordx4 v[220:223], v[120:121], off offset:192
	s_nop 0
	global_load_dwordx4 v[232:235], v[128:129], off offset:128
	s_nop 0
	s_nop 0
	s_nop 0
	global_load_dwordx4 v[224:227], v[128:129], off offset:192
	s_nop 0
	s_nop 0
	s_nop 0
	s_nop 3
	s_nop 0
	s_nop 1
	s_nop 0
	s_nop 0
	s_nop 0
	s_nop 4
	s_nop 0
	s_nop 0
	s_nop 0
	s_nop 4
	s_nop 0
	s_nop 0
	s_nop 0
	s_nop 2
	s_nop 0
	s_nop 1
	s_nop 0
	s_nop 0
	s_nop 0
	s_nop 5
	s_nop 0
	s_nop 0
	s_nop 7
	s_nop 0
	s_waitcnt vmcnt(0)
	s_nop 0
	s_nop 0
	s_nop 0
	v_mfma_f32_16x16x32_bf16 v[64:67], v[236:239], v[212:215], v[64:67]
	v_mfma_f32_16x16x32_bf16 v[52:55], v[152:155], v[212:215], v[52:55]
	v_mfma_f32_16x16x32_bf16 v[96:99], v[168:171], v[212:215], v[96:99]
	v_mfma_f32_16x16x32_bf16 v[24:27], v[176:179], v[212:215], v[24:27]
	s_nop 0
	v_mfma_f32_16x16x32_bf16 v[12:15], v[236:239], v[232:235], v[12:15]
	v_mfma_f32_16x16x32_bf16 v[28:31], v[152:155], v[232:235], v[28:31]
	v_mfma_f32_16x16x32_bf16 v[44:47], v[204:207], v[180:183], v[44:47]
	v_mfma_f32_16x16x32_bf16 v[16:19], v[216:219], v[180:183], v[16:19]
	v_mfma_f32_16x16x32_bf16 v[36:39], v[168:171], v[232:235], v[36:39]
	v_mfma_f32_16x16x32_bf16 v[48:51], v[164:167], v[180:183], v[68:71]
	v_mfma_f32_16x16x32_bf16 v[68:71], v[172:175], v[180:183], v[80:83]
	s_nop 3
	ds_write_b128 v10, v[44:47]
	s_nop 1
	ds_write_b128 v10, v[48:51] offset:64
	ds_write_b128 v10, v[68:71] offset:128
	v_mfma_f32_16x16x32_bf16 v[56:59], v[204:207], v[208:211], v[56:59]
	v_mfma_f32_16x16x32_bf16 v[76:79], v[172:175], v[208:211], v[88:91]
	v_mfma_f32_16x16x32_bf16 v[40:43], v[164:167], v[208:211], v[40:43]
	ds_write_b128 v10, v[16:19] offset:192
	s_nop 4
	ds_write_b128 v10, v[56:59] offset:4352
	s_nop 0
	ds_write_b128 v10, v[40:43] offset:4416
	v_mfma_f32_16x16x32_bf16 v[20:23], v[216:219], v[208:211], v[20:23]
	v_mfma_f32_16x16x32_bf16 v[32:35], v[176:179], v[232:235], v[32:35]
	v_mfma_f32_16x16x32_bf16 v[64:67], v[204:207], v[220:223], v[64:67]
	ds_write_b128 v10, v[76:79] offset:4480
	s_nop 4
	ds_write_b128 v10, v[20:23] offset:4544
	s_nop 0
	ds_write_b128 v10, v[64:67] offset:8704
	v_mfma_f32_16x16x32_bf16 v[52:55], v[164:167], v[220:223], v[52:55]
	s_nop 0
	v_mfma_f32_16x16x32_bf16 v[12:15], v[204:207], v[224:227], v[12:15]
	v_mfma_f32_16x16x32_bf16 v[80:83], v[172:175], v[220:223], v[96:99]
	v_mfma_f32_16x16x32_bf16 v[16:19], v[164:167], v[224:227], v[28:31]
	v_mfma_f32_16x16x32_bf16 v[24:27], v[216:219], v[220:223], v[24:27]
	s_nop 2
	ds_write_b128 v10, v[52:55] offset:8768
	s_nop 1
	ds_write_b128 v10, v[80:83] offset:8832
	s_nop 0
	ds_write_b128 v10, v[24:27] offset:8896
	v_mfma_f32_16x16x32_bf16 v[20:23], v[172:175], v[224:227], v[36:39]
	ds_write_b128 v10, v[12:15] offset:13056
	ds_write_b128 v10, v[16:19] offset:13120
	s_nop 5
	ds_write_b128 v10, v[20:23] offset:13184
	v_mfma_f32_16x16x32_bf16 v[12:15], v[216:219], v[224:227], v[32:35]
	s_nop 7
	ds_write_b128 v10, v[12:15] offset:13248
	s_waitcnt lgkmcnt(0)
	s_barrier
	s_and_saveexec_b64 s[4:5], vcc
	s_cbranch_execz .LBB0_141
	v_add_u32_e32 v0, s38, v9
	s_mov_b64 s[38:39], 0
	v_mov_b32_e32 v11, v8
	v_mov_b32_e32 v12, v6

; #define LAS __attribute__((address_space(3)))
; #define MFMA16(a, b, c) __builtin_amdgcn_mfma_f32_16x16x32_bf16((a), (b), (c), 0, 0, 0)
; template <int MT, int NT, class Epi>
; __device__ __forceinline__ void tail_splitk(LAS unsigned char* lds, const bf16_t* A, const bf16_t* Bt, int K, int row_base, int n_rt, int col_base, int n_ct, int it0, const Epi& E) {
;     ...
;         const bf16_t* ap = A + (size_t)(r0 + fr) * K + fq * 8 + w * nks * 32; const bf16_t* bp = Bt + (size_t)(c0 + fr) * K + fq * 8 + w * nks * 32;
; #pragma unroll 4
;         for (int ks = 0; ks < nks; ++ks) {
;             bf16x8 af[MT], bfv[NT];
; #pragma unroll
;             for (int mt = 0; mt < MT; ++mt) af[mt] = *(const bf16x8*)(ap + (size_t)mt * 16 * K + ks * 32);
; #pragma unroll
;             for (int nt = 0; nt < NT; ++nt) bfv[nt] = *(const bf16x8*)(bp + (size_t)nt * 16 * K + ks * 32);
; #pragma unroll
;             for (int mt = 0; mt < MT; ++mt)
; #pragma unroll
;                 for (int nt = 0; nt < NT; ++nt) acc[mt][nt] = MFMA16(bfv[nt], af[mt], acc[mt][nt]);
;         }
;         LAS float* pw = (LAS float*)(lds + w * WB);
; #pragma unroll
;         for (int mt = 0; mt < MT; ++mt)
; #pragma unroll
;             for (int nt = 0; nt < NT; ++nt) *(LAS f32x4*)(pw + (16 * mt + fr) * RS + 16 * nt + 4 * fq) = acc[mt][nt];
;         __syncthreads();
.LBB0_148:
	s_mul_hi_i32 s0, s35, 0x7e07e07f
	s_lshr_b32 s1, s0, 31
	s_ashr_i32 s0, s0, 6
	s_add_i32 s0, s0, s1
	s_lshl_b32 s53, s0, 4
	s_mulk_i32 s0, 0x82
	s_sub_i32 s0, s35, s0
	s_lshl_b32 s52, s0, 7
	v_or_b32_e32 v6, s52, v25
	v_ashrrev_i32_e32 v7, 31, v6
	v_lshlrev_b64 v[8:9], 11, v[6:7]
	s_add_i32 s0, s53, 0x1c00
	v_lshl_add_u64 v[20:21], v[2:3], 0, v[8:9]
	v_or_b32_e32 v6, s0, v25
	v_add_co_u32_e64 v18, s[0:1], s64, v20
	v_ashrrev_i32_e32 v7, 31, v6
	s_nop 0
	v_addc_co_u32_e64 v19, s[0:1], 0, v21, s[0:1]
	v_lshlrev_b64 v[6:7], 11, v[6:7]
	v_add_co_u32_e64 v16, s[0:1], s33, v20
	v_lshl_add_u64 v[6:7], v[4:5], 0, v[6:7]
	s_nop 0
	v_addc_co_u32_e64 v17, s[0:1], 0, v21, s[0:1]
	global_load_dwordx4 v[80:83], v[6:7], off
	global_load_dwordx4 v[84:87], v[6:7], off offset:64
	s_nop 0
	v_add_co_u32_e64 v14, s[0:1], s6, v20
	s_mov_b32 s4, 0x28000
	s_nop 0
	v_addc_co_u32_e64 v15, s[0:1], 0, v21, s[0:1]
	s_mov_b32 s0, 0x20000
	s_nop 0
	v_add_co_u32_e64 v12, s[0:1], s0, v20
	v_add_co_u32_e64 v10, s[38:39], s4, v20
	global_load_dwordx4 v[88:91], v[20:21], off
	global_load_dwordx4 v[92:95], v[18:19], off
	v_addc_co_u32_e64 v13, s[0:1], 0, v21, s[0:1]
	v_addc_co_u32_e64 v11, s[0:1], 0, v21, s[38:39]
	s_mov_b32 s4, 0x30000
	s_mov_b32 s0, 0x38000
	v_add_co_u32_e64 v8, s[40:41], s4, v20
	v_add_co_u32_e64 v22, s[0:1], s0, v20
	s_nop 0
	v_addc_co_u32_e64 v9, s[38:39], 0, v21, s[40:41]
	v_addc_co_u32_e64 v23, s[0:1], 0, v21, s[0:1]
	global_load_dwordx4 v[96:99], v[16:17], off
	global_load_dwordx4 v[100:103], v[14:15], off
	global_load_dwordx4 v[104:107], v[12:13], off
	global_load_dwordx4 v[108:111], v[10:11], off
	global_load_dwordx4 v[112:115], v[8:9], off
	global_load_dwordx4 v[116:119], v[22:23], off
	global_load_dwordx4 v[120:123], v[20:21], off offset:64
	global_load_dwordx4 v[124:127], v[18:19], off offset:64
	s_nop 0
	s_nop 0
	s_nop 0
	global_load_dwordx4 v[148:151], v[14:15], off offset:64
	s_nop 0
	s_nop 0
	global_load_dwordx4 v[152:155], v[16:17], off offset:64
	s_nop 0
	global_load_dwordx4 v[164:167], v[12:13], off offset:64
	s_nop 0
	s_nop 0
	global_load_dwordx4 v[168:171], v[10:11], off offset:64
	s_nop 0
	global_load_dwordx4 v[172:175], v[8:9], off offset:64
	global_load_dwordx4 v[176:179], v[22:23], off offset:64
	s_nop 0
	global_load_dwordx4 v[180:183], v[6:7], off offset:128
	s_nop 0
	s_nop 0
	global_load_dwordx4 v[184:187], v[18:19], off offset:128
	s_nop 0
	global_load_dwordx4 v[204:207], v[20:21], off offset:128
	s_nop 0
	global_load_dwordx4 v[208:211], v[16:17], off offset:128
	s_nop 0
	s_nop 0
	global_load_dwordx4 v[212:215], v[14:15], off offset:128
	s_nop 0
	global_load_dwordx4 v[216:219], v[12:13], off offset:128
	s_nop 0
	global_load_dwordx4 v[220:223], v[10:11], off offset:128
	s_nop 0
	s_nop 0
	global_load_dwordx4 v[224:227], v[8:9], off offset:128
	global_load_dwordx4 v[228:231], v[6:7], off offset:192
	s_nop 0
	global_load_dwordx4 v[232:235], v[8:9], off offset:192
	s_nop 0
	global_load_dwordx4 v[236:239], v[22:23], off offset:128
	s_nop 0
	s_waitcnt vmcnt(0)
	s_nop 0
	s_nop 0
	s_nop 0
	v_mfma_f32_16x16x32_bf16 v[32:35], v[80:83], v[88:91], 0
	v_mfma_f32_16x16x32_bf16 v[36:39], v[80:83], v[92:95], 0
	v_mfma_f32_16x16x32_bf16 v[44:47], v[80:83], v[100:103], 0
	v_mfma_f32_16x16x32_bf16 v[48:51], v[80:83], v[104:107], 0
	v_mfma_f32_16x16x32_bf16 v[52:55], v[80:83], v[108:111], 0
	v_mfma_f32_16x16x32_bf16 v[56:59], v[80:83], v[112:115], 0
	v_mfma_f32_16x16x32_bf16 v[32:35], v[84:87], v[120:123], v[32:35]
	s_nop 0
	v_mfma_f32_16x16x32_bf16 v[40:43], v[80:83], v[96:99], 0
	v_mfma_f32_16x16x32_bf16 v[28:31], v[80:83], v[116:119], 0
	s_nop 0
	v_mfma_f32_16x16x32_bf16 v[36:39], v[84:87], v[124:127], v[36:39]
	s_nop 0
	s_nop 0
	v_mfma_f32_16x16x32_bf16 v[40:43], v[84:87], v[152:155], v[40:43]
	s_nop 0
	v_mfma_f32_16x16x32_bf16 v[44:47], v[84:87], v[148:151], v[44:47]
	s_nop 0
	s_nop 0
	v_mfma_f32_16x16x32_bf16 v[48:51], v[84:87], v[164:167], v[48:51]
	s_nop 0
	s_nop 0
	v_mfma_f32_16x16x32_bf16 v[56:59], v[84:87], v[172:175], v[56:59]
	s_nop 0
	v_mfma_f32_16x16x32_bf16 v[52:55], v[84:87], v[168:171], v[52:55]
	s_nop 0
	v_mfma_f32_16x16x32_bf16 v[28:31], v[84:87], v[176:179], v[28:31]
	s_nop 0
	s_nop 0
	v_mfma_f32_16x16x32_bf16 v[32:35], v[180:183], v[204:207], v[32:35]
	s_nop 0
	v_mfma_f32_16x16x32_bf16 v[36:39], v[180:183], v[184:187], v[36:39]
	s_nop 0
	v_mfma_f32_16x16x32_bf16 v[40:43], v[180:183], v[208:211], v[40:43]
	s_nop 0
	s_nop 0
	v_mfma_f32_16x16x32_bf16 v[44:47], v[180:183], v[212:215], v[44:47]
	s_nop 0
	s_nop 0
	s_nop 0
	v_mfma_f32_16x16x32_bf16 v[48:51], v[180:183], v[216:219], v[48:51]
	s_nop 0
	v_mfma_f32_16x16x32_bf16 v[52:55], v[180:183], v[220:223], v[52:55]
	global_load_dwordx4 v[88:91], v[20:21], off offset:192
	s_nop 0
	global_load_dwordx4 v[92:95], v[18:19], off offset:192
	s_nop 0
	s_nop 0
	global_load_dwordx4 v[100:103], v[16:17], off offset:192
	s_nop 0
	global_load_dwordx4 v[104:107], v[14:15], off offset:192
	s_nop 0
	s_nop 2
	global_load_dwordx4 v[108:111], v[12:13], off offset:192
	s_nop 0
	global_load_dwordx4 v[112:115], v[10:11], off offset:192
	s_nop 0
	s_nop 0
	s_nop 2
	global_load_dwordx4 v[120:123], v[22:23], off offset:192
	s_nop 0
	s_nop 0
	s_nop 0
	s_nop 5
	s_nop 0
	s_nop 0
	s_nop 0
	s_nop 5
	s_nop 0
	s_nop 0
	s_nop 0
	s_nop 7
	s_nop 0
	s_waitcnt vmcnt(0)
	s_nop 0
	s_nop 0
	s_nop 0
	v_mfma_f32_16x16x32_bf16 v[56:59], v[180:183], v[224:227], v[56:59]
	s_nop 0
	s_nop 0
	s_nop 0
	v_mfma_f32_16x16x32_bf16 v[18:21], v[228:231], v[92:95], v[36:39]
	s_nop 2
	s_nop 0
	s_nop 0
	s_nop 0
	v_mfma_f32_16x16x32_bf16 v[14:17], v[228:231], v[104:107], v[44:47]
	s_nop 2
	s_nop 0
	v_mfma_f32_16x16x32_bf16 v[28:31], v[180:183], v[236:239], v[28:31]
	v_mfma_f32_16x16x32_bf16 v[32:35], v[228:231], v[88:91], v[32:35]
	v_mfma_f32_16x16x32_bf16 v[36:39], v[228:231], v[108:111], v[48:51]
	v_mfma_f32_16x16x32_bf16 v[40:43], v[228:231], v[100:103], v[40:43]
	s_nop 5
	ds_write_b128 v27, v[32:35]
	ds_write_b128 v27, v[18:21] offset:1280
	ds_write_b128 v27, v[40:43] offset:2560
	ds_write_b128 v27, v[14:17] offset:3840
	v_mfma_f32_16x16x32_bf16 v[10:13], v[228:231], v[112:115], v[52:55]
	v_mfma_f32_16x16x32_bf16 v[6:9], v[228:231], v[232:235], v[56:59]
	ds_write_b128 v27, v[36:39] offset:5120
	s_nop 5
	ds_write_b128 v27, v[10:13] offset:6400
	ds_write_b128 v27, v[6:9] offset:7680
	s_nop 0
	v_mfma_f32_16x16x32_bf16 v[6:9], v[228:231], v[120:123], v[28:31]
	s_nop 7
	ds_write_b128 v27, v[6:9] offset:8960
	s_waitcnt lgkmcnt(0)
	s_barrier
	s_and_saveexec_b64 s[4:5], vcc
	s_cbranch_execz .LBB0_147
	v_add_u32_e32 v6, s53, v26
	s_mov_b64 s[38:39], 0
	v_mov_b32_e32 v7, v0
	v_mov_b32_e32 v8, v24

; __device__ __forceinline__ float softplus_(float x) { return fmaxf(x, 0.f) + __logf(1.f + __expf(-fabsf(x))); }
; __device__ __forceinline__ void gla_qk_item(const Ctx& P, int l, int wi, LAS unsigned char* wl, int lane) {
;     ...
;     float run = 0.f;
; #pragma unroll 1
;     for (int t = 0; t < 64; ++t) {
;         if (t < L) { float zg = bg;
; #pragma unroll
;             for (int r = 0; r < 16; ++r) zg += __int_as_float(__builtin_amdgcn_readlane(__float_as_int(gv[r]), t)) * wg[r];
;             run += -softplus_(-zg) * (1.f / 16.f); }
;         BC[t * 64 + lane] = run;
.LBB0_267:
	s_or_b64 exec, exec, s[0:1]
	s_waitcnt vmcnt(0)
	v_lshlrev_b32_e32 v28, 16, v6
	v_and_b32_e32 v6, 0xffff0000, v6
	v_lshlrev_b32_e32 v29, 16, v7
	v_and_b32_e32 v7, 0xffff0000, v7
	v_lshlrev_b32_e32 v30, 16, v8
	v_and_b32_e32 v8, 0xffff0000, v8
	v_lshlrev_b32_e32 v31, 16, v9
	v_and_b32_e32 v9, 0xffff0000, v9
	v_lshlrev_b32_e32 v32, 16, v2
	v_and_b32_e32 v2, 0xffff0000, v2
	v_lshlrev_b32_e32 v33, 16, v3
	v_and_b32_e32 v3, 0xffff0000, v3
	v_lshlrev_b32_e32 v34, 16, v4
	v_and_b32_e32 v4, 0xffff0000, v4
	v_lshlrev_b32_e32 v35, 16, v5
	v_and_b32_e32 v5, 0xffff0000, v5
	v_mov_b32_e32 v36, v104
	s_mov_b32 s15, 0xbfb8aa3b
	s_mov_b32 s22, 0x3f317217
	s_mov_b32 s23, 0x7f800000
	s_waitcnt lgkmcnt(0)
.Lqk_top:
	s_add_i32 s94, s14, 1
	s_add_i32 s95, s14, 2
	s_add_i32 s96, s14, 3
	s_cmp_ge_u32 s14, s38
	s_cbranch_scc1 .Lqk_store
	v_readlane_b32 s0, v28, s14
	v_readlane_b32 s1, v28, s94
	v_readlane_b32 s100, v28, s95
	v_readlane_b32 s101, v28, s96
	v_fma_f32 v42, s0, v18, v26
	v_fma_f32 v46, s1, v18, v26
	v_fma_f32 v50, s100, v18, v26
	v_fma_f32 v54, s101, v18, v26
	v_readlane_b32 s0, v6, s14
	v_readlane_b32 s1, v6, s94
	v_readlane_b32 s100, v6, s95
	v_readlane_b32 s101, v6, s96
	v_fmac_f32_e32 v42, s0, v19
	v_fmac_f32_e32 v46, s1, v19
	v_fmac_f32_e32 v50, s100, v19
	v_fmac_f32_e32 v54, s101, v19
	v_readlane_b32 s0, v29, s14
	v_readlane_b32 s1, v29, s94
	v_readlane_b32 s100, v29, s95
	v_readlane_b32 s101, v29, s96
	v_fmac_f32_e32 v42, s0, v20
	v_fmac_f32_e32 v46, s1, v20
	v_fmac_f32_e32 v50, s100, v20
	v_fmac_f32_e32 v54, s101, v20
	v_readlane_b32 s0, v7, s14
	v_readlane_b32 s1, v7, s94
	v_readlane_b32 s100, v7, s95
	v_readlane_b32 s101, v7, s96
	v_fmac_f32_e32 v42, s0, v21
	v_fmac_f32_e32 v46, s1, v21
	v_fmac_f32_e32 v50, s100, v21
	v_fmac_f32_e32 v54, s101, v21
	v_readlane_b32 s0, v30, s14
	v_readlane_b32 s1, v30, s94
	v_readlane_b32 s100, v30, s95
	v_readlane_b32 s101, v30, s96
	v_fmac_f32_e32 v42, s0, v22
	v_fmac_f32_e32 v46, s1, v22
	v_fmac_f32_e32 v50, s100, v22
	v_fmac_f32_e32 v54, s101, v22
	v_readlane_b32 s0, v8, s14
	v_readlane_b32 s1, v8, s94
	v_readlane_b32 s100, v8, s95
	v_readlane_b32 s101, v8, s96
	v_fmac_f32_e32 v42, s0, v23
	v_fmac_f32_e32 v46, s1, v23
	v_fmac_f32_e32 v50, s100, v23
	v_fmac_f32_e32 v54, s101, v23
	v_readlane_b32 s0, v31, s14
	v_readlane_b32 s1, v31, s94
	v_readlane_b32 s100, v31, s95
	v_readlane_b32 s101, v31, s96
	v_fmac_f32_e32 v42, s0, v24
	v_fmac_f32_e32 v46, s1, v24
	v_fmac_f32_e32 v50, s100, v24
	v_fmac_f32_e32 v54, s101, v24
	v_readlane_b32 s0, v9, s14
	v_readlane_b32 s1, v9, s94
	v_readlane_b32 s100, v9, s95
	v_readlane_b32 s101, v9, s96
	v_fmac_f32_e32 v42, s0, v25
	v_fmac_f32_e32 v46, s1, v25
	v_fmac_f32_e32 v50, s100, v25
	v_fmac_f32_e32 v54, s101, v25
	v_readlane_b32 s86, v32, s14
	v_readlane_b32 s87, v2, s14
	v_readlane_b32 s88, v32, s94
	v_readlane_b32 s89, v2, s94
	v_readlane_b32 s90, v32, s95
	v_readlane_b32 s91, v2, s95
	v_readlane_b32 s92, v32, s96
	v_readlane_b32 s93, v2, s96
	v_pk_mul_f32 v[44:45], v[10:11], s[86:87]
	v_pk_mul_f32 v[48:49], v[10:11], s[88:89]
	v_pk_mul_f32 v[52:53], v[10:11], s[90:91]
	v_pk_mul_f32 v[56:57], v[10:11], s[92:93]
	v_add_f32_e32 v42, v42, v44
	v_add_f32_e32 v46, v46, v48
	v_add_f32_e32 v50, v50, v52
	v_add_f32_e32 v54, v54, v56
	v_add_f32_e32 v42, v42, v45
	v_add_f32_e32 v46, v46, v49
	v_add_f32_e32 v50, v50, v53
	v_add_f32_e32 v54, v54, v57
	v_readlane_b32 s86, v33, s14
	v_readlane_b32 s87, v3, s14
	v_readlane_b32 s88, v33, s94
	v_readlane_b32 s89, v3, s94
	v_readlane_b32 s90, v33, s95
	v_readlane_b32 s91, v3, s95
	v_readlane_b32 s92, v33, s96
	v_readlane_b32 s93, v3, s96
	v_pk_mul_f32 v[44:45], v[12:13], s[86:87]
	v_pk_mul_f32 v[48:49], v[12:13], s[88:89]
	v_pk_mul_f32 v[52:53], v[12:13], s[90:91]
	v_pk_mul_f32 v[56:57], v[12:13], s[92:93]
	v_add_f32_e32 v42, v42, v44
	v_add_f32_e32 v46, v46, v48
	v_add_f32_e32 v50, v50, v52
	v_add_f32_e32 v54, v54, v56
	v_add_f32_e32 v42, v42, v45
	v_add_f32_e32 v46, v46, v49
	v_add_f32_e32 v50, v50, v53
	v_add_f32_e32 v54, v54, v57
	v_readlane_b32 s86, v34, s14
; __device__ __forceinline__ float softplus_(float x) { return fmaxf(x, 0.f) + __logf(1.f + __expf(-fabsf(x))); }
; __device__ __forceinline__ void gla_qk_item(const Ctx& P, int l, int wi, LAS unsigned char* wl, int lane) {
;     ...
;     float run = 0.f;
; #pragma unroll 1
;     for (int t = 0; t < 64; ++t) {
;         if (t < L) { float zg = bg;
; #pragma unroll
;             for (int r = 0; r < 16; ++r) zg += __int_as_float(__builtin_amdgcn_readlane(__float_as_int(gv[r]), t)) * wg[r];
;             run += -softplus_(-zg) * (1.f / 16.f); }
;         BC[t * 64 + lane] = run;
;     }
	v_readlane_b32 s87, v4, s14
	v_readlane_b32 s88, v34, s94
	v_readlane_b32 s89, v4, s94
	v_readlane_b32 s90, v34, s95
	v_readlane_b32 s91, v4, s95
	v_readlane_b32 s92, v34, s96
	v_readlane_b32 s93, v4, s96
	v_pk_mul_f32 v[44:45], v[14:15], s[86:87]
	v_pk_mul_f32 v[48:49], v[14:15], s[88:89]
	v_pk_mul_f32 v[52:53], v[14:15], s[90:91]
	v_pk_mul_f32 v[56:57], v[14:15], s[92:93]
	v_add_f32_e32 v42, v42, v44
	v_add_f32_e32 v46, v46, v48
	v_add_f32_e32 v50, v50, v52
	v_add_f32_e32 v54, v54, v56
	v_add_f32_e32 v42, v42, v45
	v_add_f32_e32 v46, v46, v49
	v_add_f32_e32 v50, v50, v53
	v_add_f32_e32 v54, v54, v57
	v_readlane_b32 s86, v35, s14
	v_readlane_b32 s87, v5, s14
	v_readlane_b32 s88, v35, s94
	v_readlane_b32 s89, v5, s94
	v_readlane_b32 s90, v35, s95
	v_readlane_b32 s91, v5, s95
	v_readlane_b32 s92, v35, s96
	v_readlane_b32 s93, v5, s96
	v_pk_mul_f32 v[44:45], v[16:17], s[86:87]
	v_pk_mul_f32 v[48:49], v[16:17], s[88:89]
	v_pk_mul_f32 v[52:53], v[16:17], s[90:91]
	v_pk_mul_f32 v[56:57], v[16:17], s[92:93]
	v_add_f32_e32 v42, v42, v44
	v_add_f32_e32 v46, v46, v48
	v_add_f32_e32 v50, v50, v52
	v_add_f32_e32 v54, v54, v56
	v_add_f32_e32 v42, v42, v45
	v_add_f32_e32 v46, v46, v49
	v_add_f32_e32 v50, v50, v53
	v_add_f32_e32 v54, v54, v57
	v_mul_f32_e64 v44, |v42|, s15
	v_mul_f32_e64 v48, |v46|, s15
	v_mul_f32_e64 v52, |v50|, s15
	v_mul_f32_e64 v56, |v54|, s15
	v_exp_f32_e32 v44, v44
	v_exp_f32_e32 v48, v48
	v_exp_f32_e32 v52, v52
	v_exp_f32_e32 v56, v56
	v_max_f32_e64 v43, -v42, 0
	v_max_f32_e64 v47, -v46, 0
	v_max_f32_e64 v51, -v50, 0
	v_max_f32_e64 v55, -v54, 0
	v_add_f32_e32 v44, 1.0, v44
	v_add_f32_e32 v48, 1.0, v48
	v_add_f32_e32 v52, 1.0, v52
	v_add_f32_e32 v56, 1.0, v56
	v_cmp_gt_f32_e64 s[86:87], s66, v44
	v_cmp_gt_f32_e64 s[88:89], s66, v48
	v_cmp_gt_f32_e64 s[90:91], s66, v52
	v_cmp_gt_f32_e64 s[92:93], s66, v56
	v_cndmask_b32_e64 v45, 0, 32, s[86:87]
	v_cndmask_b32_e64 v49, 0, 32, s[88:89]
	v_cndmask_b32_e64 v53, 0, 32, s[90:91]
	v_cndmask_b32_e64 v57, 0, 32, s[92:93]
	v_ldexp_f32 v44, v44, v45
	v_ldexp_f32 v48, v48, v49
	v_ldexp_f32 v52, v52, v53
	v_ldexp_f32 v56, v56, v57
	v_log_f32_e32 v44, v44
	v_log_f32_e32 v48, v48
	v_log_f32_e32 v52, v52
	v_log_f32_e32 v56, v56
	v_mul_f32_e32 v45, 0x3f317217, v44
	v_mul_f32_e32 v49, 0x3f317217, v48
	v_mul_f32_e32 v53, 0x3f317217, v52
	v_mul_f32_e32 v57, 0x3f317217, v56
	v_fma_f32 v45, v44, s22, -v45
	v_fma_f32 v49, v48, s22, -v49
	v_fma_f32 v53, v52, s22, -v53
	v_fma_f32 v57, v56, s22, -v57
	v_fmac_f32_e32 v45, 0x3377d1cf, v44
	v_fmac_f32_e32 v49, 0x3377d1cf, v48
	v_fmac_f32_e32 v53, 0x3377d1cf, v52
	v_fmac_f32_e32 v57, 0x3377d1cf, v56
	v_fmac_f32_e32 v45, 0x3f317217, v44
	v_fmac_f32_e32 v49, 0x3f317217, v48
	v_fmac_f32_e32 v53, 0x3f317217, v52
	v_fmac_f32_e32 v57, 0x3f317217, v56
	v_cmp_lt_f32_e64 s[94:95], |v44|, s23
	v_cmp_lt_f32_e64 s[96:97], |v48|, s23
	v_cmp_lt_f32_e64 s[0:1], |v52|, s23
	v_cmp_lt_f32_e64 s[100:101], |v56|, s23
	v_cndmask_b32_e64 v44, v44, v45, s[94:95]
	v_cndmask_b32_e64 v48, v48, v49, s[96:97]
	v_cndmask_b32_e64 v52, v52, v53, s[0:1]
	v_cndmask_b32_e64 v56, v56, v57, s[100:101]
	v_cndmask_b32_e64 v45, 0, v195, s[86:87]
	v_cndmask_b32_e64 v49, 0, v195, s[88:89]
	v_cndmask_b32_e64 v53, 0, v195, s[90:91]
	v_cndmask_b32_e64 v57, 0, v195, s[92:93]
	v_sub_f32_e32 v44, v44, v45
	v_sub_f32_e32 v48, v48, v49
	v_sub_f32_e32 v52, v52, v53
	v_sub_f32_e32 v56, v56, v57
	v_add_f32_e32 v43, v43, v44
	v_add_f32_e32 v47, v47, v48
	v_add_f32_e32 v51, v51, v52
	v_add_f32_e32 v55, v55, v56
	v_fmac_f32_e32 v27, 0xbd800000, v43
	ds_write_b32 v36, v27
	v_fmac_f32_e32 v27, 0xbd800000, v47
	ds_write_b32 v36, v27 offset:256
	v_fmac_f32_e32 v27, 0xbd800000, v51
	ds_write_b32 v36, v27 offset:512
	v_fmac_f32_e32 v27, 0xbd800000, v55
	ds_write_b32 v36, v27 offset:768
	s_branch .Lqk_next
.Lqk_store:
	ds_write_b32 v36, v27
	ds_write_b32 v36, v27 offset:256
	ds_write_b32 v36, v27 offset:512
	ds_write_b32 v36, v27 offset:768
.Lqk_next:
	v_add_u32_e32 v36, 0x400, v36
	s_add_i32 s14, s14, 4
	s_cmp_eq_u32 s14, 64
	s_cbranch_scc0 .Lqk_top
	s_waitcnt lgkmcnt(0)

; #define LAS __attribute__((address_space(3)))
; #define MFMA16(a, b, c) __builtin_amdgcn_mfma_f32_16x16x32_bf16((a), (b), (c), 0, 0, 0)
; __device__ __forceinline__ void gla_prompt_unit(const Ctx& P, int l, int b, int h, int eh, LAS unsigned char* lds) {
;     ...
;         const int L = c == 0 ? 16 : 64, row0 = b * TP + (c == 0 ? 0 : 16 + 64 * (c - 1));
;         { bf16x8 ka[2][4], qv[2][4];
; #pragma unroll
;           for (int ii = 0; ii < 2; ++ii) { const int idx = 2 * w + ii, si = idx >> 2, ti = idx & 3;
; #pragma unroll
;               for (int ks = 0; ks < 4; ++ks) { const int sw = ((ks * 4 + fq) ^ fr) * 16; ka[ii][ks] = *(const LAS bf16x8*)(kb + (16 * si + fr) * QS + sw); qv[ii][ks] = *(const LAS bf16x8*)(qb + (16 * ti + fr) * QS + sw); } }
;           __builtin_amdgcn_sched_barrier(0);
;           f32x4 acc[2];
; #pragma unroll
;           for (int ii = 0; ii < 2; ++ii) acc[ii] = (f32x4){0.f, 0.f, 0.f, 0.f};
; #pragma unroll
;           for (int ks = 0; ks < 4; ++ks)
; #pragma unroll
;               for (int ii = 0; ii < 2; ++ii) acc[ii] = MFMA16(ka[ii][ks], qv[ii][ks], acc[ii]);
; #pragma unroll
;           for (int ii = 0; ii < 2; ++ii) { const int idx = 2 * w + ii, si = idx >> 2, ti = idx & 3;
;               const int t = 16 * ti + fr;
;               float a0 = acc[ii][0], a1 = acc[ii][1], a2 = acc[ii][2], a3 = acc[ii][3]; const int s0 = 16 * si + fq * 4;
;               if (s0 + 0 > t) a0 = 0.f; if (s0 + 1 > t) a1 = 0.f; if (s0 + 2 > t) a2 = 0.f; if (s0 + 3 > t) a3 = 0.f;
;               u32x2 ow; ow.x = pk2(a0, a1); ow.y = pk2(a2, a3);
;               *(LAS u32x2*)(Abuf + t * KS + s0 * 2) = ow; } }
;         __syncthreads();
;         f32x4 o[4];
;         { bf16x8 af[2][4]; u32x2 q0[4][4], q1[4][4];
; #pragma unroll
;           for (int ks = 0; ks < 2; ++ks)
; #pragma unroll
;               for (int tt = 0; tt < 4; ++tt) af[ks][tt] = *(const LAS bf16x8*)(Abuf + (16 * tt + fr) * KS + ks * 64 + fq * 16);
; #pragma unroll
;           for (int ks = 0; ks < 4; ++ks)
; #pragma unroll
;               for (int tt = 0; tt < 4; ++tt) { q0[ks][tt] = *(const LAS u32x2*)(qb + (16 * tt + fr) * QS + (((4 * ks + (fq >> 1)) ^ fr) * 16) + 8 * (fq & 1)); q1[ks][tt] = *(const LAS u32x2*)(qb + (16 * tt + fr) * QS + (((4 * ks + 2 + (fq >> 1)) ^ fr) * 16) + 8 * (fq & 1)); }
;           bf16x8 sa[4];
; #pragma unroll
.LBB0_582:
	s_mul_i32 s23, s22, 0xc000
	s_add_i32 s23, s23, 0
	v_add_u32_e32 v186, s23, v90
	v_add_u32_e32 v117, s23, v89
	v_add_u32_e32 v126, s28, v186
	v_add_u32_e32 v58, v117, v91
	v_add_u32_e32 v62, v126, v91
	v_add_u32_e32 v66, v117, v92
	v_add_u32_e32 v70, v126, v92
	v_add_u32_e32 v118, v117, v93
	v_add_u32_e32 v122, v126, v93
	v_add_u32_e32 v117, v117, v94
	v_add_u32_e32 v142, v126, v94
	ds_read_b128 v[58:61], v58 offset:16384
	ds_read_b128 v[62:65], v62
	ds_read_b128 v[66:69], v66 offset:16384
	ds_read_b128 v[70:73], v70
	ds_read_b128 v[118:121], v118 offset:16384
	ds_read_b128 v[122:125], v122
	ds_read_b128 v[126:129], v117 offset:16384
	ds_read_b128 v[142:145], v142
	v_add_u32_e32 v117, s29, v186
	v_add_u32_e32 v146, v117, v91
	v_add_u32_e32 v150, v117, v92
	v_add_u32_e32 v154, v117, v93
	ds_read_b128 v[146:149], v146
	ds_read_b128 v[150:153], v150
	v_add_u32_e32 v117, v117, v94
	ds_read_b128 v[154:157], v154
	ds_read_b128 v[158:161], v117
	s_waitcnt lgkmcnt(0)
	v_mfma_f32_16x16x32_bf16 v[62:65], v[58:61], v[62:65], 0
	v_add3_u32 v117, v186, v105, v88
	v_add3_u32 v174, v186, v104, v88
	v_add3_u32 v187, v186, v107, v88
	v_mfma_f32_16x16x32_bf16 v[58:61], v[58:61], v[146:149], 0
	v_cvt_pk_bf16_f32 v228, v54, v55
	v_cvt_pk_bf16_f32 v229, v56, v57
	v_cvt_pk_bf16_f32 v230, v50, v51
	v_mfma_f32_16x16x32_bf16 v[62:65], v[66:69], v[70:73], v[62:65]
	v_cvt_pk_bf16_f32 v231, v52, v53
	v_cvt_pk_bf16_f32 v232, v46, v47
	v_cvt_pk_bf16_f32 v233, v48, v49
	v_mfma_f32_16x16x32_bf16 v[58:61], v[66:69], v[150:153], v[58:61]
	v_cvt_pk_bf16_f32 v234, v42, v43
	v_cvt_pk_bf16_f32 v235, v44, v45
	v_cvt_pk_bf16_f32 v236, v38, v39
	v_mfma_f32_16x16x32_bf16 v[62:65], v[118:121], v[122:125], v[62:65]
	v_cvt_pk_bf16_f32 v237, v40, v41
	v_cvt_pk_bf16_f32 v238, v34, v35
	v_cvt_pk_bf16_f32 v239, v36, v37
	v_mfma_f32_16x16x32_bf16 v[58:61], v[118:121], v[154:157], v[58:61]
	v_cvt_pk_bf16_f32 v240, v30, v31
	v_cvt_pk_bf16_f32 v241, v32, v33
	v_cvt_pk_bf16_f32 v242, v26, v27
	v_mfma_f32_16x16x32_bf16 v[62:65], v[126:129], v[142:145], v[62:65]
	v_cvt_pk_bf16_f32 v243, v28, v29
	v_mfma_f32_16x16x32_bf16 v[58:61], v[126:129], v[158:161], v[58:61]
	v_add3_u32 v158, v186, v103, v88
	s_nop 4
	v_cndmask_b32_e64 v62, v62, 0, s[42:43]
	v_cndmask_b32_e64 v63, 0, v63, s[44:45]
	v_cndmask_b32_e64 v64, v64, 0, s[46:47]
	v_cndmask_b32_e64 v65, v65, 0, s[48:49]
	v_cndmask_b32_e64 v58, v58, 0, s[50:51]
	v_cndmask_b32_e64 v59, 0, v59, s[52:53]
	v_cndmask_b32_e64 v60, v60, 0, s[54:55]
	v_cndmask_b32_e64 v61, v61, 0, s[56:57]
	v_cvt_pk_bf16_f32 v62, v62, v63
	v_cvt_pk_bf16_f32 v63, v64, v65
	v_cvt_pk_bf16_f32 v58, v58, v59
	v_cvt_pk_bf16_f32 v59, v60, v61
	ds_write_b64 v113, v[62:63]
	ds_write_b64 v112, v[58:59]
	s_waitcnt lgkmcnt(0)
	s_barrier
	ds_read_b128 v[58:61], v0
	ds_read_b128 v[62:65], v0 offset:64
	ds_read_b128 v[66:69], v0 offset:2304
	ds_read_b128 v[70:73], v0 offset:2368
	ds_read_b128 v[118:121], v0 offset:4608
	ds_read_b128 v[122:125], v0 offset:4672
	ds_read_b128 v[126:129], v0 offset:6912
	ds_read_b128 v[142:145], v0 offset:6976
	ds_read2st64_b64 v[146:149], v117 offset1:8
	ds_read2st64_b64 v[150:153], v158 offset1:8
	ds_read2st64_b64 v[154:157], v117 offset0:16 offset1:24
	ds_read2st64_b64 v[158:161], v158 offset0:16 offset1:24
	v_add3_u32 v117, v186, v106, v88
	ds_read2st64_b64 v[162:165], v117 offset1:8
	ds_read2st64_b64 v[166:169], v174 offset1:8
	ds_read2st64_b64 v[170:173], v117 offset0:16 offset1:24
	ds_read2st64_b64 v[174:177], v174 offset0:16 offset1:24
	v_add3_u32 v117, v186, v109, v88
	ds_read2st64_b64 v[178:181], v117 offset1:8
	ds_read2st64_b64 v[182:185], v187 offset1:8
	ds_read2st64_b64 v[204:207], v117 offset0:16 offset1:24
	ds_read2st64_b64 v[208:211], v187 offset0:16 offset1:24
	v_add3_u32 v117, v186, v110, v88
	v_add3_u32 v186, v186, v108, v88
	ds_read2st64_b64 v[212:215], v117 offset1:8
	ds_read2st64_b64 v[216:219], v186 offset1:8
	ds_read2st64_b64 v[220:223], v117 offset0:16 offset1:24
	ds_read2st64_b64 v[224:227], v186 offset0:16 offset1:24
	s_waitcnt lgkmcnt(14)
	v_mfma_f32_16x16x32_bf16 v[58:61], v[22:25], v[58:61], 0
	v_mfma_f32_16x16x32_bf16 v[66:69], v[22:25], v[66:69], 0
	v_mfma_f32_16x16x32_bf16 v[118:121], v[22:25], v[118:121], 0
	v_mfma_f32_16x16x32_bf16 v[126:129], v[22:25], v[126:129], 0
	v_mfma_f32_16x16x32_bf16 v[58:61], v[18:21], v[62:65], v[58:61]
	v_mfma_f32_16x16x32_bf16 v[62:65], v[18:21], v[70:73], v[66:69]
	v_mfma_f32_16x16x32_bf16 v[66:69], v[18:21], v[122:125], v[118:121]
	v_mfma_f32_16x16x32_bf16 v[70:73], v[18:21], v[142:145], v[126:129]
	s_nop 2
	v_mov_b32_e32 v118, v146
	v_mov_b32_e32 v119, v147
	v_mov_b32_e32 v120, v150
	v_mov_b32_e32 v121, v151
	v_mov_b32_e32 v150, v148
	v_mov_b32_e32 v151, v149
	v_mfma_f32_16x16x32_bf16 v[58:61], v[228:231], v[118:121], v[58:61]
	s_waitcnt lgkmcnt(13)
	v_mov_b32_e32 v118, v154
	v_mov_b32_e32 v119, v155
	s_waitcnt lgkmcnt(12)
	v_mov_b32_e32 v120, v158
	v_mov_b32_e32 v121, v159
	v_mov_b32_e32 v158, v156
	v_mov_b32_e32 v159, v157
	v_mfma_f32_16x16x32_bf16 v[62:65], v[228:231], v[150:153], v[62:65]
	v_mfma_f32_16x16x32_bf16 v[66:69], v[228:231], v[118:121], v[66:69]
	s_waitcnt lgkmcnt(11)
	v_mov_b32_e32 v118, v162
	v_mov_b32_e32 v119, v163
	s_waitcnt lgkmcnt(10)
	v_mov_b32_e32 v120, v166
	v_mfma_f32_16x16x32_bf16 v[70:73], v[228:231], v[158:161], v[70:73]
	v_mov_b32_e32 v121, v167
	v_mov_b32_e32 v166, v164
	v_mov_b32_e32 v167, v165
	v_mfma_f32_16x16x32_bf16 v[58:61], v[232:235], v[118:121], v[58:61]
	s_waitcnt lgkmcnt(9)
; #define LAS __attribute__((address_space(3)))
; #define MFMA16(a, b, c) __builtin_amdgcn_mfma_f32_16x16x32_bf16((a), (b), (c), 0, 0, 0)
; __device__ __forceinline__ void gla_prompt_unit(const Ctx& P, int l, int b, int h, int eh, LAS unsigned char* lds) {
;     ...
;           for (int ks = 0; ks < 4; ++ks)
; #pragma unroll
;               for (int tt = 0; tt < 4; ++tt) { u32x4 qw; qw.x = q0[ks][tt].x; qw.y = q0[ks][tt].y; qw.z = q1[ks][tt].x; qw.w = q1[ks][tt].y;
;                   o[tt] = MFMA16(sa[ks], __builtin_bit_cast(bf16x8, qw), o[tt]); } }
;         __builtin_amdgcn_sched_barrier(0);
;         { const LAS float* dp = DECL + bufc * 128; bf16x8 kf[8][2]; f32x4 dv[8];
; #pragma unroll
;           for (int dt = 0; dt < 8; ++dt) { dv[dt] = *(const LAS f32x4*)(dp + 16 * dt + fq * 4);
; #pragma unroll
;               for (int ks = 0; ks < 2; ++ks) kf[dt][ks] = *(const LAS bf16x8*)(eb + (16 * dt + fr) * ES + (((ks * 4 + fq) ^ (fr & 7)) * 16)); }
;           __builtin_amdgcn_sched_barrier(0);
; #pragma unroll
;           for (int dt = 0; dt < 8; ++dt) S[dt] = S[dt] * dv[dt];
; #pragma unroll
;           for (int ks = 0; ks < 2; ++ks)
; #pragma unroll
;               for (int dt = 0; dt < 8; ++dt) S[dt] = MFMA16(kf[dt][ks], vt[ks], S[dt]); }
;         __builtin_amdgcn_sched_barrier(0);
;         if (grp == ((c + 1) & 1)) asm volatile("s_waitcnt vmcnt(0)" ::: "memory");
	v_mov_b32_e32 v118, v170
	v_mov_b32_e32 v119, v171
	s_waitcnt lgkmcnt(8)
	v_mov_b32_e32 v120, v174
	v_mov_b32_e32 v121, v175
	v_mov_b32_e32 v174, v172
	v_mov_b32_e32 v175, v173
	v_mfma_f32_16x16x32_bf16 v[62:65], v[232:235], v[166:169], v[62:65]
	v_mfma_f32_16x16x32_bf16 v[66:69], v[232:235], v[118:121], v[66:69]
	s_waitcnt lgkmcnt(7)
	v_mov_b32_e32 v118, v178
	v_mov_b32_e32 v119, v179
	s_waitcnt lgkmcnt(6)
	v_mov_b32_e32 v120, v182
	v_mfma_f32_16x16x32_bf16 v[70:73], v[232:235], v[174:177], v[70:73]
	v_mov_b32_e32 v121, v183
	v_mov_b32_e32 v182, v180
	v_mov_b32_e32 v183, v181
	v_mfma_f32_16x16x32_bf16 v[58:61], v[236:239], v[118:121], v[58:61]
	s_waitcnt lgkmcnt(5)
	v_mov_b32_e32 v118, v204
	v_mov_b32_e32 v119, v205
	s_waitcnt lgkmcnt(4)
	v_mov_b32_e32 v120, v208
	v_mov_b32_e32 v121, v209
	v_mov_b32_e32 v208, v206
	v_mov_b32_e32 v209, v207
	v_mfma_f32_16x16x32_bf16 v[62:65], v[236:239], v[182:185], v[62:65]
	v_mfma_f32_16x16x32_bf16 v[118:121], v[236:239], v[118:121], v[66:69]
	v_mfma_f32_16x16x32_bf16 v[122:125], v[236:239], v[208:211], v[70:73]
	s_waitcnt lgkmcnt(3)
	s_nop 0
	v_mov_b32_e32 v66, v212
	v_mov_b32_e32 v67, v213
	s_waitcnt lgkmcnt(2)
	v_mov_b32_e32 v68, v216
	v_mov_b32_e32 v69, v217
	v_mov_b32_e32 v216, v214
	v_mov_b32_e32 v217, v215
	v_mfma_f32_16x16x32_bf16 v[70:73], v[240:243], v[66:69], v[58:61]
	s_waitcnt lgkmcnt(1)
	s_nop 1
	v_mov_b32_e32 v58, v220
	v_mov_b32_e32 v59, v221
	s_waitcnt lgkmcnt(0)
	v_mov_b32_e32 v60, v224
	v_mov_b32_e32 v61, v225
	v_mov_b32_e32 v224, v222
	v_mov_b32_e32 v225, v223
	v_mfma_f32_16x16x32_bf16 v[66:69], v[240:243], v[216:219], v[62:65]
	v_mfma_f32_16x16x32_bf16 v[62:65], v[240:243], v[58:61], v[118:121]
	v_mfma_f32_16x16x32_bf16 v[58:61], v[240:243], v[224:227], v[122:125]
	v_add_u32_e32 v126, s23, v100
	v_add_u32_e32 v146, s23, v101
	v_add_u32_e32 v162, s23, v102
	v_lshl_add_u32 v117, s22, 9, v85
	v_add_u32_e32 v118, s23, v99
	v_add_u32_e32 v127, v126, v97
	v_add_u32_e32 v142, v126, v98
	v_add_u32_e32 v147, v146, v97
	v_add_u32_e32 v150, v146, v98
	v_add_u32_e32 v163, v162, v97
	v_add_u32_e32 v166, v162, v98
	v_add_u32_e32 v186, v118, v97
	v_add_u32_e32 v187, v118, v98
	ds_read_b128 v[118:121], v117
	ds_read_b128 v[122:125], v117 offset:64
	ds_read_b128 v[126:129], v127 offset:32768
	ds_read_b128 v[142:145], v142 offset:32768
	ds_read_b128 v[146:149], v147 offset:32768
	ds_read_b128 v[150:153], v150 offset:32768
	ds_read_b128 v[154:157], v117 offset:128
	ds_read_b128 v[158:161], v117 offset:192
	ds_read_b128 v[162:165], v163 offset:32768
	ds_read_b128 v[166:169], v166 offset:32768
	ds_read_b128 v[170:173], v186 offset:32768
	ds_read_b128 v[174:177], v186 offset:40960
	ds_read_b128 v[178:181], v117 offset:256
	ds_read_b128 v[182:185], v117 offset:320
	ds_read_b128 v[204:207], v187 offset:40960
	ds_read_b128 v[208:211], v187 offset:43008
	ds_read_b128 v[212:215], v186 offset:43008
	ds_read_b128 v[216:219], v186 offset:45056
	ds_read_b128 v[220:223], v117 offset:384
	ds_read_b128 v[224:227], v117 offset:448
	ds_read_b128 v[228:231], v187 offset:32768
	ds_read_b128 v[232:235], v186 offset:47104
	ds_read_b128 v[236:239], v187 offset:45056
	ds_read_b128 v[240:243], v187 offset:47104
	s_waitcnt lgkmcnt(14)
	v_pk_mul_f32 v[56:57], v[56:57], v[120:121]
	v_pk_mul_f32 v[54:55], v[54:55], v[118:119]
	v_pk_mul_f32 v[52:53], v[52:53], v[124:125]
	v_pk_mul_f32 v[50:51], v[50:51], v[122:123]
	v_pk_mul_f32 v[48:49], v[48:49], v[156:157]
	v_pk_mul_f32 v[46:47], v[46:47], v[154:155]
	v_pk_mul_f32 v[44:45], v[44:45], v[160:161]
	v_pk_mul_f32 v[42:43], v[42:43], v[158:159]
	s_waitcnt lgkmcnt(11)
	v_pk_mul_f32 v[40:41], v[40:41], v[180:181]
	v_pk_mul_f32 v[38:39], v[38:39], v[178:179]
	s_waitcnt lgkmcnt(10)
	v_pk_mul_f32 v[36:37], v[36:37], v[184:185]
	v_pk_mul_f32 v[34:35], v[34:35], v[182:183]
	s_waitcnt lgkmcnt(5)
	v_pk_mul_f32 v[32:33], v[32:33], v[222:223]
	v_pk_mul_f32 v[30:31], v[30:31], v[220:221]
	s_waitcnt lgkmcnt(4)
	v_pk_mul_f32 v[28:29], v[28:29], v[226:227]
	v_pk_mul_f32 v[26:27], v[26:27], v[224:225]
	v_mfma_f32_16x16x32_bf16 v[54:57], v[170:173], v[22:25], v[54:57]
	v_mfma_f32_16x16x32_bf16 v[50:53], v[126:129], v[22:25], v[50:53]
	v_mfma_f32_16x16x32_bf16 v[46:49], v[146:149], v[22:25], v[46:49]
	v_mfma_f32_16x16x32_bf16 v[42:45], v[162:165], v[22:25], v[42:45]
	v_mfma_f32_16x16x32_bf16 v[38:41], v[174:177], v[22:25], v[38:41]
	v_mfma_f32_16x16x32_bf16 v[34:37], v[212:215], v[22:25], v[34:37]
	v_mfma_f32_16x16x32_bf16 v[30:33], v[216:219], v[22:25], v[30:33]
	s_waitcnt lgkmcnt(2)
	v_mfma_f32_16x16x32_bf16 v[22:25], v[232:235], v[22:25], v[26:29]
	v_mfma_f32_16x16x32_bf16 v[54:57], v[228:231], v[18:21], v[54:57]
	v_mfma_f32_16x16x32_bf16 v[50:53], v[142:145], v[18:21], v[50:53]
	v_mfma_f32_16x16x32_bf16 v[46:49], v[150:153], v[18:21], v[46:49]
	v_mfma_f32_16x16x32_bf16 v[42:45], v[166:169], v[18:21], v[42:45]
	v_mfma_f32_16x16x32_bf16 v[38:41], v[204:207], v[18:21], v[38:41]
	v_mfma_f32_16x16x32_bf16 v[34:37], v[208:211], v[18:21], v[34:37]
	s_waitcnt lgkmcnt(1)
	v_mfma_f32_16x16x32_bf16 v[30:33], v[236:239], v[18:21], v[30:33]
	s_waitcnt lgkmcnt(0)
	v_mfma_f32_16x16x32_bf16 v[26:29], v[240:243], v[18:21], v[22:25]
	s_and_b32 s22, s61, 1
	s_cmp_lg_u32 s35, s22
	s_cbranch_scc1 .LBB0_584
	s_waitcnt vmcnt(0)

; #define LAS __attribute__((address_space(3)))
; __device__ __forceinline__ void gla_prompt_unit(const Ctx& P, int l, int b, int h, int eh, LAS unsigned char* lds) {
;     ...
;         const int bufn = bufc == 2 ? 0 : bufc + 1, bufnn = bufn == 2 ? 0 : bufn + 1;
;         LAS unsigned char* qb = lds + bufc * BUFB; LAS unsigned char* kb = qb + 16384; LAS unsigned char* eb = qb + 32768;
;         vt[0] = vtA[0]; vt[1] = vtA[1]; vtA[0] = vtB[0]; vtA[1] = vtB[1];
;     ...
;         __syncthreads();
;         bufc = bufn;
.LBB0_594:
	s_or_b64 exec, exec, s[22:23]
	s_mov_b64 s[22:23], 0x10000
	v_lshl_add_u64 v[76:77], v[76:77], 0, s[22:23]
	s_mov_b64 s[22:23], 0x20000
	v_lshl_add_u64 v[78:79], v[78:79], 0, s[22:23]
	s_add_i32 s61, s61, 1
	s_add_i32 s68, s68, 64
	s_mov_b64 s[22:23], 0x800
	s_cmpk_lg_i32 s68, 0x780
	v_lshl_add_u64 v[80:81], v[80:81], 0, s[22:23]
	s_waitcnt vmcnt(8) lgkmcnt(0)
	s_barrier
	s_cbranch_scc0 .LBB0_596
	v_mov_b64_e32 v[20:21], v[4:5]
	v_mov_b64_e32 v[24:25], v[8:9]
	v_mov_b64_e32 v[18:19], v[2:3]
	v_mov_b64_e32 v[22:23], v[6:7]
	v_mov_b64_e32 v[2:3], v[10:11]
	v_mov_b64_e32 v[6:7], v[14:15]
	v_mov_b64_e32 v[4:5], v[12:13]
	v_mov_b64_e32 v[8:9], v[16:17]
	v_mov_b32_e32 v111, v115
	s_mov_b32 s22, s60
	s_branch .LBB0_578

; __device__ __forceinline__ float bflo(unsigned w) { return __uint_as_float(w << 16); }
; __device__ __forceinline__ float bfhi(unsigned w) { return __uint_as_float(w & 0xffff0000u); }
; __device__ __forceinline__ unsigned pk2(float lo, float hi) { f32x2 v = {lo, hi}; bf16x2_t b = __builtin_convertvector(v, bf16x2_t); return __builtin_bit_cast(unsigned, b); }
; __device__ __forceinline__ float sigm(float x) { return __builtin_amdgcn_rcpf(1.f + __expf(-x)); }
;     template <int QPR> __device__ __forceinline__ void tailq(int row, int c, const f32x4 v, int) const { quad(row, c, v); }
;     __device__ __forceinline__ void quad(int row, int c, f32x4 v) const {
;         const u32x2 gw = *(const u32x2*)(Z + (size_t)row * NZ + ZC_MA + c);
;         v[0] *= sigm(bflo(gw.x)); v[1] *= sigm(bfhi(gw.x)); v[2] *= sigm(bflo(gw.y)); v[3] *= sigm(bfhi(gw.y));
;         u32x2 w; w.x = pk2(v[0], v[1]); w.y = pk2(v[2], v[3]); *(u32x2*)(T + (size_t)row * D + c) = w; }
;     template <int QPR> __device__ __forceinline__ void tailq(int row, int c, const f32x4 v, int) const { quad(row, c, v); }
;     __device__ __forceinline__ void operator()(const f32x4 (&acc)[2][2][4][2], const pg8::Unit& u, int wr, int wc, int fr, int fq) const {
;         const int row0 = u.pm * 256 + wr * 64 + fr, col0 = u.pn * 256 + wc * 32 + 4 * fq;
; #pragma unroll
;         for (int ai = 0; ai < 2; ++ai)
; #pragma unroll
;             for (int m = 0; m < 4; ++m) { const int row = row0 + ai * 128 + m * 16;
; #pragma unroll
;                 for (int bj = 0; bj < 2; ++bj)
; #pragma unroll
;                     for (int n = 0; n < 2; ++n) { const int c = col0 + bj * 128 + n * 16;
;                         quad(row, c, acc[ai][bj][m][n]); } }
.LBB0_709:
	v_lshl_add_u32 v156, s84, 8, v158
	v_lshl_or_b32 v157, s83, 8, v160
	v_mov_b64_e32 v[240:241], s[34:35]
	v_mad_u64_u32 v[236:237], s[4:5], v156, s67, v[240:241]
	v_lshlrev_b32_e32 v186, 1, v157
	v_add_u32_e32 v186, 0x2800, v186
	v_mov_b32_e32 v187, 0
	v_lshl_add_u64 v[236:237], v[236:237], 0, v[186:187]
	v_lshlrev_b32_e32 v240, 11, v156
	v_lshl_add_u32 v240, v157, 1, v240
	v_mov_b32_e32 v241, 0
	v_lshl_add_u64 v[238:239], s[22:23], 0, v[240:241]
	s_mov_b64 s[4:5], 0x3a000
	global_load_dwordx2 v[148:149], v[236:237], off
	global_load_dwordx2 v[150:151], v[236:237], off offset:32
	global_load_dwordx2 v[152:153], v[236:237], off offset:256
	global_load_dwordx2 v[154:155], v[236:237], off offset:288
	v_lshl_add_u64 v[236:237], v[236:237], 0, s[4:5]
	global_load_dwordx2 v[162:163], v[236:237], off
	global_load_dwordx2 v[164:165], v[236:237], off offset:32
	global_load_dwordx2 v[166:167], v[236:237], off offset:256
	global_load_dwordx2 v[168:169], v[236:237], off offset:288
	v_lshl_add_u64 v[236:237], v[236:237], 0, s[4:5]
	global_load_dwordx2 v[170:171], v[236:237], off
	global_load_dwordx2 v[172:173], v[236:237], off offset:32
	global_load_dwordx2 v[174:175], v[236:237], off offset:256
	global_load_dwordx2 v[176:177], v[236:237], off offset:288
	v_lshl_add_u64 v[236:237], v[236:237], 0, s[4:5]
	global_load_dwordx2 v[178:179], v[236:237], off
	global_load_dwordx2 v[180:181], v[236:237], off offset:32
	global_load_dwordx2 v[182:183], v[236:237], off offset:256
	global_load_dwordx2 v[184:185], v[236:237], off offset:288
	s_mov_b64 s[4:5], 0x122000
	v_lshl_add_u64 v[236:237], v[236:237], 0, s[4:5]
	s_mov_b64 s[4:5], 0x3a000
	global_load_dwordx2 v[204:205], v[236:237], off
	global_load_dwordx2 v[206:207], v[236:237], off offset:32
	global_load_dwordx2 v[208:209], v[236:237], off offset:256
	global_load_dwordx2 v[210:211], v[236:237], off offset:288
	v_lshl_add_u64 v[236:237], v[236:237], 0, s[4:5]
	global_load_dwordx2 v[212:213], v[236:237], off
	global_load_dwordx2 v[214:215], v[236:237], off offset:32
	global_load_dwordx2 v[216:217], v[236:237], off offset:256
	global_load_dwordx2 v[218:219], v[236:237], off offset:288
	v_lshl_add_u64 v[236:237], v[236:237], 0, s[4:5]
	global_load_dwordx2 v[220:221], v[236:237], off
	global_load_dwordx2 v[222:223], v[236:237], off offset:32
	global_load_dwordx2 v[224:225], v[236:237], off offset:256
	global_load_dwordx2 v[226:227], v[236:237], off offset:288
	v_lshl_add_u64 v[236:237], v[236:237], 0, s[4:5]
	global_load_dwordx2 v[228:229], v[236:237], off
	global_load_dwordx2 v[230:231], v[236:237], off offset:32
	global_load_dwordx2 v[232:233], v[236:237], off offset:256
	global_load_dwordx2 v[234:235], v[236:237], off offset:288
	s_mov_b64 s[4:5], 0x8000
	s_waitcnt vmcnt(31)
	v_lshlrev_b32_e32 v156, 16, v148
	v_and_b32_e32 v157, 0xffff0000, v148
	v_lshlrev_b32_e32 v186, 16, v149
	v_and_b32_e32 v187, 0xffff0000, v149
	v_mul_f32_e32 v156, 0xbfb8aa3b, v156
	v_mul_f32_e32 v157, 0xbfb8aa3b, v157
	v_mul_f32_e32 v186, 0xbfb8aa3b, v186
	v_mul_f32_e32 v187, 0xbfb8aa3b, v187
	v_exp_f32_e32 v156, v156
	v_exp_f32_e32 v157, v157
	v_exp_f32_e32 v186, v186
	v_exp_f32_e32 v187, v187
	v_add_f32_e32 v156, 1.0, v156
	v_add_f32_e32 v157, 1.0, v157
	v_add_f32_e32 v186, 1.0, v186
	v_add_f32_e32 v187, 1.0, v187
	v_rcp_f32_e32 v156, v156
	v_rcp_f32_e32 v157, v157
	v_rcp_f32_e32 v186, v186
	v_rcp_f32_e32 v187, v187
	v_pk_mul_f32 v[126:127], v[126:127], v[156:157]
	v_pk_mul_f32 v[128:129], v[128:129], v[186:187]
	v_cvt_pk_bf16_f32 v148, v126, v127
	v_cvt_pk_bf16_f32 v149, v128, v129
	global_store_dwordx2 v[238:239], v[148:149], off
	s_waitcnt vmcnt(31)
	v_lshlrev_b32_e32 v156, 16, v150
	v_and_b32_e32 v157, 0xffff0000, v150
	v_lshlrev_b32_e32 v186, 16, v151
	v_and_b32_e32 v187, 0xffff0000, v151
	v_mul_f32_e32 v156, 0xbfb8aa3b, v156
	v_mul_f32_e32 v157, 0xbfb8aa3b, v157
	v_mul_f32_e32 v186, 0xbfb8aa3b, v186
	v_mul_f32_e32 v187, 0xbfb8aa3b, v187
	v_exp_f32_e32 v156, v156
	v_exp_f32_e32 v157, v157
	v_exp_f32_e32 v186, v186
	v_exp_f32_e32 v187, v187
	v_add_f32_e32 v156, 1.0, v156
	v_add_f32_e32 v157, 1.0, v157
	v_add_f32_e32 v186, 1.0, v186
	v_add_f32_e32 v187, 1.0, v187
	v_rcp_f32_e32 v156, v156
	v_rcp_f32_e32 v157, v157
	v_rcp_f32_e32 v186, v186
	v_rcp_f32_e32 v187, v187
	v_pk_mul_f32 v[122:123], v[122:123], v[156:157]
	v_pk_mul_f32 v[124:125], v[124:125], v[186:187]
	v_cvt_pk_bf16_f32 v150, v122, v123
	v_cvt_pk_bf16_f32 v151, v124, v125
	global_store_dwordx2 v[238:239], v[150:151], off offset:32
	s_waitcnt vmcnt(31)
	v_lshlrev_b32_e32 v156, 16, v152
	v_and_b32_e32 v157, 0xffff0000, v152
	v_lshlrev_b32_e32 v186, 16, v153
	v_and_b32_e32 v187, 0xffff0000, v153
	v_mul_f32_e32 v156, 0xbfb8aa3b, v156
	v_mul_f32_e32 v157, 0xbfb8aa3b, v157
	v_mul_f32_e32 v186, 0xbfb8aa3b, v186
	v_mul_f32_e32 v187, 0xbfb8aa3b, v187
	v_exp_f32_e32 v156, v156
	v_exp_f32_e32 v157, v157
	v_exp_f32_e32 v186, v186
	v_exp_f32_e32 v187, v187
	v_add_f32_e32 v156, 1.0, v156
	v_add_f32_e32 v157, 1.0, v157
	v_add_f32_e32 v186, 1.0, v186
	v_add_f32_e32 v187, 1.0, v187
	v_rcp_f32_e32 v156, v156
	v_rcp_f32_e32 v157, v157
	v_rcp_f32_e32 v186, v186
	v_rcp_f32_e32 v187, v187
	v_pk_mul_f32 v[118:119], v[118:119], v[156:157]
	v_pk_mul_f32 v[120:121], v[120:121], v[186:187]
	v_cvt_pk_bf16_f32 v152, v118, v119
	v_cvt_pk_bf16_f32 v153, v120, v121
	global_store_dwordx2 v[238:239], v[152:153], off offset:256
	s_waitcnt vmcnt(31)
; __device__ __forceinline__ float bflo(unsigned w) { return __uint_as_float(w << 16); }
; __device__ __forceinline__ float bfhi(unsigned w) { return __uint_as_float(w & 0xffff0000u); }
; __device__ __forceinline__ unsigned pk2(float lo, float hi) { f32x2 v = {lo, hi}; bf16x2_t b = __builtin_convertvector(v, bf16x2_t); return __builtin_bit_cast(unsigned, b); }
; __device__ __forceinline__ float sigm(float x) { return __builtin_amdgcn_rcpf(1.f + __expf(-x)); }
;     template <int QPR> __device__ __forceinline__ void tailq(int row, int c, const f32x4 v, int) const { quad(row, c, v); }
;     __device__ __forceinline__ void quad(int row, int c, f32x4 v) const {
;         const u32x2 gw = *(const u32x2*)(Z + (size_t)row * NZ + ZC_MA + c);
;         v[0] *= sigm(bflo(gw.x)); v[1] *= sigm(bfhi(gw.x)); v[2] *= sigm(bflo(gw.y)); v[3] *= sigm(bfhi(gw.y));
;         u32x2 w; w.x = pk2(v[0], v[1]); w.y = pk2(v[2], v[3]); *(u32x2*)(T + (size_t)row * D + c) = w; }
;     template <int QPR> __device__ __forceinline__ void tailq(int row, int c, const f32x4 v, int) const { quad(row, c, v); }
;     __device__ __forceinline__ void operator()(const f32x4 (&acc)[2][2][4][2], const pg8::Unit& u, int wr, int wc, int fr, int fq) const {
;         const int row0 = u.pm * 256 + wr * 64 + fr, col0 = u.pn * 256 + wc * 32 + 4 * fq;
; #pragma unroll
;         for (int ai = 0; ai < 2; ++ai)
; #pragma unroll
;             for (int m = 0; m < 4; ++m) { const int row = row0 + ai * 128 + m * 16;
; #pragma unroll
;                 for (int bj = 0; bj < 2; ++bj)
; #pragma unroll
;                     for (int n = 0; n < 2; ++n) { const int c = col0 + bj * 128 + n * 16;
;                         quad(row, c, acc[ai][bj][m][n]); } }
	v_lshlrev_b32_e32 v156, 16, v154
	v_and_b32_e32 v157, 0xffff0000, v154
	v_lshlrev_b32_e32 v186, 16, v155
	v_and_b32_e32 v187, 0xffff0000, v155
	v_mul_f32_e32 v156, 0xbfb8aa3b, v156
	v_mul_f32_e32 v157, 0xbfb8aa3b, v157
	v_mul_f32_e32 v186, 0xbfb8aa3b, v186
	v_mul_f32_e32 v187, 0xbfb8aa3b, v187
	v_exp_f32_e32 v156, v156
	v_exp_f32_e32 v157, v157
	v_exp_f32_e32 v186, v186
	v_exp_f32_e32 v187, v187
	v_add_f32_e32 v156, 1.0, v156
	v_add_f32_e32 v157, 1.0, v157
	v_add_f32_e32 v186, 1.0, v186
	v_add_f32_e32 v187, 1.0, v187
	v_rcp_f32_e32 v156, v156
	v_rcp_f32_e32 v157, v157
	v_rcp_f32_e32 v186, v186
	v_rcp_f32_e32 v187, v187
	v_pk_mul_f32 v[114:115], v[114:115], v[156:157]
	v_pk_mul_f32 v[116:117], v[116:117], v[186:187]
	v_cvt_pk_bf16_f32 v154, v114, v115
	v_cvt_pk_bf16_f32 v155, v116, v117
	global_store_dwordx2 v[238:239], v[154:155], off offset:288
	v_lshl_add_u64 v[238:239], v[238:239], 0, s[4:5]
	s_waitcnt vmcnt(31)
	v_lshlrev_b32_e32 v156, 16, v162
	v_and_b32_e32 v157, 0xffff0000, v162
	v_lshlrev_b32_e32 v186, 16, v163
	v_and_b32_e32 v187, 0xffff0000, v163
	v_mul_f32_e32 v156, 0xbfb8aa3b, v156
	v_mul_f32_e32 v157, 0xbfb8aa3b, v157
	v_mul_f32_e32 v186, 0xbfb8aa3b, v186
	v_mul_f32_e32 v187, 0xbfb8aa3b, v187
	v_exp_f32_e32 v156, v156
	v_exp_f32_e32 v157, v157
	v_exp_f32_e32 v186, v186
	v_exp_f32_e32 v187, v187
	v_add_f32_e32 v156, 1.0, v156
	v_add_f32_e32 v157, 1.0, v157
	v_add_f32_e32 v186, 1.0, v186
	v_add_f32_e32 v187, 1.0, v187
	v_rcp_f32_e32 v156, v156
	v_rcp_f32_e32 v157, v157
	v_rcp_f32_e32 v186, v186
	v_rcp_f32_e32 v187, v187
	v_pk_mul_f32 v[110:111], v[110:111], v[156:157]
	v_pk_mul_f32 v[112:113], v[112:113], v[186:187]
	v_cvt_pk_bf16_f32 v162, v110, v111
	v_cvt_pk_bf16_f32 v163, v112, v113
	global_store_dwordx2 v[238:239], v[162:163], off
	s_waitcnt vmcnt(31)
	v_lshlrev_b32_e32 v156, 16, v164
	v_and_b32_e32 v157, 0xffff0000, v164
	v_lshlrev_b32_e32 v186, 16, v165
	v_and_b32_e32 v187, 0xffff0000, v165
	v_mul_f32_e32 v156, 0xbfb8aa3b, v156
	v_mul_f32_e32 v157, 0xbfb8aa3b, v157
	v_mul_f32_e32 v186, 0xbfb8aa3b, v186
	v_mul_f32_e32 v187, 0xbfb8aa3b, v187
	v_exp_f32_e32 v156, v156
	v_exp_f32_e32 v157, v157
	v_exp_f32_e32 v186, v186
	v_exp_f32_e32 v187, v187
	v_add_f32_e32 v156, 1.0, v156
	v_add_f32_e32 v157, 1.0, v157
	v_add_f32_e32 v186, 1.0, v186
	v_add_f32_e32 v187, 1.0, v187
	v_rcp_f32_e32 v156, v156
	v_rcp_f32_e32 v157, v157
	v_rcp_f32_e32 v186, v186
	v_rcp_f32_e32 v187, v187
	v_pk_mul_f32 v[106:107], v[106:107], v[156:157]
	v_pk_mul_f32 v[108:109], v[108:109], v[186:187]
	v_cvt_pk_bf16_f32 v164, v106, v107
	v_cvt_pk_bf16_f32 v165, v108, v109
	global_store_dwordx2 v[238:239], v[164:165], off offset:32
	s_waitcnt vmcnt(31)
	v_lshlrev_b32_e32 v156, 16, v166
	v_and_b32_e32 v157, 0xffff0000, v166
	v_lshlrev_b32_e32 v186, 16, v167
	v_and_b32_e32 v187, 0xffff0000, v167
	v_mul_f32_e32 v156, 0xbfb8aa3b, v156
	v_mul_f32_e32 v157, 0xbfb8aa3b, v157
	v_mul_f32_e32 v186, 0xbfb8aa3b, v186
	v_mul_f32_e32 v187, 0xbfb8aa3b, v187
	v_exp_f32_e32 v156, v156
	v_exp_f32_e32 v157, v157
	v_exp_f32_e32 v186, v186
	v_exp_f32_e32 v187, v187
	v_add_f32_e32 v156, 1.0, v156
	v_add_f32_e32 v157, 1.0, v157
	v_add_f32_e32 v186, 1.0, v186
	v_add_f32_e32 v187, 1.0, v187
	v_rcp_f32_e32 v156, v156
	v_rcp_f32_e32 v157, v157
	v_rcp_f32_e32 v186, v186
	v_rcp_f32_e32 v187, v187
	v_pk_mul_f32 v[102:103], v[102:103], v[156:157]
	v_pk_mul_f32 v[104:105], v[104:105], v[186:187]
	v_cvt_pk_bf16_f32 v166, v102, v103
	v_cvt_pk_bf16_f32 v167, v104, v105
	global_store_dwordx2 v[238:239], v[166:167], off offset:256
	s_waitcnt vmcnt(31)
	v_lshlrev_b32_e32 v156, 16, v168
	v_and_b32_e32 v157, 0xffff0000, v168
	v_lshlrev_b32_e32 v186, 16, v169
	v_and_b32_e32 v187, 0xffff0000, v169
	v_mul_f32_e32 v156, 0xbfb8aa3b, v156
	v_mul_f32_e32 v157, 0xbfb8aa3b, v157
	v_mul_f32_e32 v186, 0xbfb8aa3b, v186
	v_mul_f32_e32 v187, 0xbfb8aa3b, v187
	v_exp_f32_e32 v156, v156
	v_exp_f32_e32 v157, v157
	v_exp_f32_e32 v186, v186
	v_exp_f32_e32 v187, v187
	v_add_f32_e32 v156, 1.0, v156
	v_add_f32_e32 v157, 1.0, v157
	v_add_f32_e32 v186, 1.0, v186
	v_add_f32_e32 v187, 1.0, v187
	v_rcp_f32_e32 v156, v156
	v_rcp_f32_e32 v157, v157
	v_rcp_f32_e32 v186, v186
	v_rcp_f32_e32 v187, v187
	v_pk_mul_f32 v[98:99], v[98:99], v[156:157]
	v_pk_mul_f32 v[100:101], v[100:101], v[186:187]
	v_cvt_pk_bf16_f32 v168, v98, v99
	v_cvt_pk_bf16_f32 v169, v100, v101
	global_store_dwordx2 v[238:239], v[168:169], off offset:288
	v_lshl_add_u64 v[238:239], v[238:239], 0, s[4:5]
	s_waitcnt vmcnt(31)
	v_lshlrev_b32_e32 v156, 16, v170
	v_and_b32_e32 v157, 0xffff0000, v170
	v_lshlrev_b32_e32 v186, 16, v171
	v_and_b32_e32 v187, 0xffff0000, v171
	v_mul_f32_e32 v156, 0xbfb8aa3b, v156
	v_mul_f32_e32 v157, 0xbfb8aa3b, v157
	v_mul_f32_e32 v186, 0xbfb8aa3b, v186
	v_mul_f32_e32 v187, 0xbfb8aa3b, v187
	v_exp_f32_e32 v156, v156
	v_exp_f32_e32 v157, v157
	v_exp_f32_e32 v186, v186
	v_exp_f32_e32 v187, v187
	v_add_f32_e32 v156, 1.0, v156
	v_add_f32_e32 v157, 1.0, v157
	v_add_f32_e32 v186, 1.0, v186
	v_add_f32_e32 v187, 1.0, v187
	v_rcp_f32_e32 v156, v156
	v_rcp_f32_e32 v157, v157
	v_rcp_f32_e32 v186, v186
	v_rcp_f32_e32 v187, v187
	v_pk_mul_f32 v[94:95], v[94:95], v[156:157]
	v_pk_mul_f32 v[96:97], v[96:97], v[186:187]
	v_cvt_pk_bf16_f32 v170, v94, v95
	v_cvt_pk_bf16_f32 v171, v96, v97
	global_store_dwordx2 v[238:239], v[170:171], off
	s_waitcnt vmcnt(31)
; __device__ __forceinline__ float bflo(unsigned w) { return __uint_as_float(w << 16); }
; __device__ __forceinline__ float bfhi(unsigned w) { return __uint_as_float(w & 0xffff0000u); }
; __device__ __forceinline__ unsigned pk2(float lo, float hi) { f32x2 v = {lo, hi}; bf16x2_t b = __builtin_convertvector(v, bf16x2_t); return __builtin_bit_cast(unsigned, b); }
; __device__ __forceinline__ float sigm(float x) { return __builtin_amdgcn_rcpf(1.f + __expf(-x)); }
;     template <int QPR> __device__ __forceinline__ void tailq(int row, int c, const f32x4 v, int) const { quad(row, c, v); }
;     __device__ __forceinline__ void quad(int row, int c, f32x4 v) const {
;         const u32x2 gw = *(const u32x2*)(Z + (size_t)row * NZ + ZC_MA + c);
;         v[0] *= sigm(bflo(gw.x)); v[1] *= sigm(bfhi(gw.x)); v[2] *= sigm(bflo(gw.y)); v[3] *= sigm(bfhi(gw.y));
;         u32x2 w; w.x = pk2(v[0], v[1]); w.y = pk2(v[2], v[3]); *(u32x2*)(T + (size_t)row * D + c) = w; }
;     template <int QPR> __device__ __forceinline__ void tailq(int row, int c, const f32x4 v, int) const { quad(row, c, v); }
;     __device__ __forceinline__ void operator()(const f32x4 (&acc)[2][2][4][2], const pg8::Unit& u, int wr, int wc, int fr, int fq) const {
;         const int row0 = u.pm * 256 + wr * 64 + fr, col0 = u.pn * 256 + wc * 32 + 4 * fq;
; #pragma unroll
;         for (int ai = 0; ai < 2; ++ai)
; #pragma unroll
;             for (int m = 0; m < 4; ++m) { const int row = row0 + ai * 128 + m * 16;
; #pragma unroll
;                 for (int bj = 0; bj < 2; ++bj)
; #pragma unroll
;                     for (int n = 0; n < 2; ++n) { const int c = col0 + bj * 128 + n * 16;
;                         quad(row, c, acc[ai][bj][m][n]); } }
	v_lshlrev_b32_e32 v156, 16, v172
	v_and_b32_e32 v157, 0xffff0000, v172
	v_lshlrev_b32_e32 v186, 16, v173
	v_and_b32_e32 v187, 0xffff0000, v173
	v_mul_f32_e32 v156, 0xbfb8aa3b, v156
	v_mul_f32_e32 v157, 0xbfb8aa3b, v157
	v_mul_f32_e32 v186, 0xbfb8aa3b, v186
	v_mul_f32_e32 v187, 0xbfb8aa3b, v187
	v_exp_f32_e32 v156, v156
	v_exp_f32_e32 v157, v157
	v_exp_f32_e32 v186, v186
	v_exp_f32_e32 v187, v187
	v_add_f32_e32 v156, 1.0, v156
	v_add_f32_e32 v157, 1.0, v157
	v_add_f32_e32 v186, 1.0, v186
	v_add_f32_e32 v187, 1.0, v187
	v_rcp_f32_e32 v156, v156
	v_rcp_f32_e32 v157, v157
	v_rcp_f32_e32 v186, v186
	v_rcp_f32_e32 v187, v187
	v_pk_mul_f32 v[90:91], v[90:91], v[156:157]
	v_pk_mul_f32 v[92:93], v[92:93], v[186:187]
	v_cvt_pk_bf16_f32 v172, v90, v91
	v_cvt_pk_bf16_f32 v173, v92, v93
	global_store_dwordx2 v[238:239], v[172:173], off offset:32
	s_waitcnt vmcnt(31)
	v_lshlrev_b32_e32 v156, 16, v174
	v_and_b32_e32 v157, 0xffff0000, v174
	v_lshlrev_b32_e32 v186, 16, v175
	v_and_b32_e32 v187, 0xffff0000, v175
	v_mul_f32_e32 v156, 0xbfb8aa3b, v156
	v_mul_f32_e32 v157, 0xbfb8aa3b, v157
	v_mul_f32_e32 v186, 0xbfb8aa3b, v186
	v_mul_f32_e32 v187, 0xbfb8aa3b, v187
	v_exp_f32_e32 v156, v156
	v_exp_f32_e32 v157, v157
	v_exp_f32_e32 v186, v186
	v_exp_f32_e32 v187, v187
	v_add_f32_e32 v156, 1.0, v156
	v_add_f32_e32 v157, 1.0, v157
	v_add_f32_e32 v186, 1.0, v186
	v_add_f32_e32 v187, 1.0, v187
	v_rcp_f32_e32 v156, v156
	v_rcp_f32_e32 v157, v157
	v_rcp_f32_e32 v186, v186
	v_rcp_f32_e32 v187, v187
	v_pk_mul_f32 v[86:87], v[86:87], v[156:157]
	v_pk_mul_f32 v[88:89], v[88:89], v[186:187]
	v_cvt_pk_bf16_f32 v174, v86, v87
	v_cvt_pk_bf16_f32 v175, v88, v89
	global_store_dwordx2 v[238:239], v[174:175], off offset:256
	s_waitcnt vmcnt(31)
	v_lshlrev_b32_e32 v156, 16, v176
	v_and_b32_e32 v157, 0xffff0000, v176
	v_lshlrev_b32_e32 v186, 16, v177
	v_and_b32_e32 v187, 0xffff0000, v177
	v_mul_f32_e32 v156, 0xbfb8aa3b, v156
	v_mul_f32_e32 v157, 0xbfb8aa3b, v157
	v_mul_f32_e32 v186, 0xbfb8aa3b, v186
	v_mul_f32_e32 v187, 0xbfb8aa3b, v187
	v_exp_f32_e32 v156, v156
	v_exp_f32_e32 v157, v157
	v_exp_f32_e32 v186, v186
	v_exp_f32_e32 v187, v187
	v_add_f32_e32 v156, 1.0, v156
	v_add_f32_e32 v157, 1.0, v157
	v_add_f32_e32 v186, 1.0, v186
	v_add_f32_e32 v187, 1.0, v187
	v_rcp_f32_e32 v156, v156
	v_rcp_f32_e32 v157, v157
	v_rcp_f32_e32 v186, v186
	v_rcp_f32_e32 v187, v187
	v_pk_mul_f32 v[82:83], v[82:83], v[156:157]
	v_pk_mul_f32 v[84:85], v[84:85], v[186:187]
	v_cvt_pk_bf16_f32 v176, v82, v83
	v_cvt_pk_bf16_f32 v177, v84, v85
	global_store_dwordx2 v[238:239], v[176:177], off offset:288
	v_lshl_add_u64 v[238:239], v[238:239], 0, s[4:5]
	s_waitcnt vmcnt(31)
	v_lshlrev_b32_e32 v156, 16, v178
	v_and_b32_e32 v157, 0xffff0000, v178
	v_lshlrev_b32_e32 v186, 16, v179
	v_and_b32_e32 v187, 0xffff0000, v179
	v_mul_f32_e32 v156, 0xbfb8aa3b, v156
	v_mul_f32_e32 v157, 0xbfb8aa3b, v157
	v_mul_f32_e32 v186, 0xbfb8aa3b, v186
	v_mul_f32_e32 v187, 0xbfb8aa3b, v187
	v_exp_f32_e32 v156, v156
	v_exp_f32_e32 v157, v157
	v_exp_f32_e32 v186, v186
	v_exp_f32_e32 v187, v187
	v_add_f32_e32 v156, 1.0, v156
	v_add_f32_e32 v157, 1.0, v157
	v_add_f32_e32 v186, 1.0, v186
	v_add_f32_e32 v187, 1.0, v187
	v_rcp_f32_e32 v156, v156
	v_rcp_f32_e32 v157, v157
	v_rcp_f32_e32 v186, v186
	v_rcp_f32_e32 v187, v187
	v_pk_mul_f32 v[78:79], v[78:79], v[156:157]
	v_pk_mul_f32 v[80:81], v[80:81], v[186:187]
	v_cvt_pk_bf16_f32 v178, v78, v79
	v_cvt_pk_bf16_f32 v179, v80, v81
	global_store_dwordx2 v[238:239], v[178:179], off
	s_waitcnt vmcnt(31)
	v_lshlrev_b32_e32 v156, 16, v180
	v_and_b32_e32 v157, 0xffff0000, v180
	v_lshlrev_b32_e32 v186, 16, v181
	v_and_b32_e32 v187, 0xffff0000, v181
	v_mul_f32_e32 v156, 0xbfb8aa3b, v156
	v_mul_f32_e32 v157, 0xbfb8aa3b, v157
	v_mul_f32_e32 v186, 0xbfb8aa3b, v186
	v_mul_f32_e32 v187, 0xbfb8aa3b, v187
	v_exp_f32_e32 v156, v156
	v_exp_f32_e32 v157, v157
	v_exp_f32_e32 v186, v186
	v_exp_f32_e32 v187, v187
	v_add_f32_e32 v156, 1.0, v156
	v_add_f32_e32 v157, 1.0, v157
	v_add_f32_e32 v186, 1.0, v186
	v_add_f32_e32 v187, 1.0, v187
	v_rcp_f32_e32 v156, v156
	v_rcp_f32_e32 v157, v157
	v_rcp_f32_e32 v186, v186
	v_rcp_f32_e32 v187, v187
	v_pk_mul_f32 v[74:75], v[74:75], v[156:157]
	v_pk_mul_f32 v[76:77], v[76:77], v[186:187]
	v_cvt_pk_bf16_f32 v180, v74, v75
	v_cvt_pk_bf16_f32 v181, v76, v77
	global_store_dwordx2 v[238:239], v[180:181], off offset:32
	s_waitcnt vmcnt(31)
	v_lshlrev_b32_e32 v156, 16, v182
	v_and_b32_e32 v157, 0xffff0000, v182
	v_lshlrev_b32_e32 v186, 16, v183
	v_and_b32_e32 v187, 0xffff0000, v183
	v_mul_f32_e32 v156, 0xbfb8aa3b, v156
	v_mul_f32_e32 v157, 0xbfb8aa3b, v157
	v_mul_f32_e32 v186, 0xbfb8aa3b, v186
	v_mul_f32_e32 v187, 0xbfb8aa3b, v187
	v_exp_f32_e32 v156, v156
	v_exp_f32_e32 v157, v157
	v_exp_f32_e32 v186, v186
	v_exp_f32_e32 v187, v187
	v_add_f32_e32 v156, 1.0, v156
	v_add_f32_e32 v157, 1.0, v157
	v_add_f32_e32 v186, 1.0, v186
	v_add_f32_e32 v187, 1.0, v187
	v_rcp_f32_e32 v156, v156
	v_rcp_f32_e32 v157, v157
	v_rcp_f32_e32 v186, v186
	v_rcp_f32_e32 v187, v187
	v_pk_mul_f32 v[70:71], v[70:71], v[156:157]
	v_pk_mul_f32 v[72:73], v[72:73], v[186:187]
	v_cvt_pk_bf16_f32 v182, v70, v71
	v_cvt_pk_bf16_f32 v183, v72, v73
	global_store_dwordx2 v[238:239], v[182:183], off offset:256
	s_waitcnt vmcnt(31)
; __device__ __forceinline__ float bflo(unsigned w) { return __uint_as_float(w << 16); }
; __device__ __forceinline__ float bfhi(unsigned w) { return __uint_as_float(w & 0xffff0000u); }
; __device__ __forceinline__ unsigned pk2(float lo, float hi) { f32x2 v = {lo, hi}; bf16x2_t b = __builtin_convertvector(v, bf16x2_t); return __builtin_bit_cast(unsigned, b); }
; __device__ __forceinline__ float sigm(float x) { return __builtin_amdgcn_rcpf(1.f + __expf(-x)); }
;     template <int QPR> __device__ __forceinline__ void tailq(int row, int c, const f32x4 v, int) const { quad(row, c, v); }
;     __device__ __forceinline__ void quad(int row, int c, f32x4 v) const {
;         const u32x2 gw = *(const u32x2*)(Z + (size_t)row * NZ + ZC_MA + c);
;         v[0] *= sigm(bflo(gw.x)); v[1] *= sigm(bfhi(gw.x)); v[2] *= sigm(bflo(gw.y)); v[3] *= sigm(bfhi(gw.y));
;         u32x2 w; w.x = pk2(v[0], v[1]); w.y = pk2(v[2], v[3]); *(u32x2*)(T + (size_t)row * D + c) = w; }
;     template <int QPR> __device__ __forceinline__ void tailq(int row, int c, const f32x4 v, int) const { quad(row, c, v); }
;     __device__ __forceinline__ void operator()(const f32x4 (&acc)[2][2][4][2], const pg8::Unit& u, int wr, int wc, int fr, int fq) const {
;         const int row0 = u.pm * 256 + wr * 64 + fr, col0 = u.pn * 256 + wc * 32 + 4 * fq;
; #pragma unroll
;         for (int ai = 0; ai < 2; ++ai)
; #pragma unroll
;             for (int m = 0; m < 4; ++m) { const int row = row0 + ai * 128 + m * 16;
; #pragma unroll
;                 for (int bj = 0; bj < 2; ++bj)
; #pragma unroll
;                     for (int n = 0; n < 2; ++n) { const int c = col0 + bj * 128 + n * 16;
;                         quad(row, c, acc[ai][bj][m][n]); } }
	v_lshlrev_b32_e32 v156, 16, v184
	v_and_b32_e32 v157, 0xffff0000, v184
	v_lshlrev_b32_e32 v186, 16, v185
	v_and_b32_e32 v187, 0xffff0000, v185
	v_mul_f32_e32 v156, 0xbfb8aa3b, v156
	v_mul_f32_e32 v157, 0xbfb8aa3b, v157
	v_mul_f32_e32 v186, 0xbfb8aa3b, v186
	v_mul_f32_e32 v187, 0xbfb8aa3b, v187
	v_exp_f32_e32 v156, v156
	v_exp_f32_e32 v157, v157
	v_exp_f32_e32 v186, v186
	v_exp_f32_e32 v187, v187
	v_add_f32_e32 v156, 1.0, v156
	v_add_f32_e32 v157, 1.0, v157
	v_add_f32_e32 v186, 1.0, v186
	v_add_f32_e32 v187, 1.0, v187
	v_rcp_f32_e32 v156, v156
	v_rcp_f32_e32 v157, v157
	v_rcp_f32_e32 v186, v186
	v_rcp_f32_e32 v187, v187
	v_pk_mul_f32 v[66:67], v[66:67], v[156:157]
	v_pk_mul_f32 v[68:69], v[68:69], v[186:187]
	v_cvt_pk_bf16_f32 v184, v66, v67
	v_cvt_pk_bf16_f32 v185, v68, v69
	global_store_dwordx2 v[238:239], v[184:185], off offset:288
	s_mov_b64 s[4:5], 0x28000
	v_lshl_add_u64 v[238:239], v[238:239], 0, s[4:5]
	s_mov_b64 s[4:5], 0x8000
	s_waitcnt vmcnt(31)
	v_lshlrev_b32_e32 v156, 16, v204
	v_and_b32_e32 v157, 0xffff0000, v204
	v_lshlrev_b32_e32 v186, 16, v205
	v_and_b32_e32 v187, 0xffff0000, v205
	v_mul_f32_e32 v156, 0xbfb8aa3b, v156
	v_mul_f32_e32 v157, 0xbfb8aa3b, v157
	v_mul_f32_e32 v186, 0xbfb8aa3b, v186
	v_mul_f32_e32 v187, 0xbfb8aa3b, v187
	v_exp_f32_e32 v156, v156
	v_exp_f32_e32 v157, v157
	v_exp_f32_e32 v186, v186
	v_exp_f32_e32 v187, v187
	v_add_f32_e32 v156, 1.0, v156
	v_add_f32_e32 v157, 1.0, v157
	v_add_f32_e32 v186, 1.0, v186
	v_add_f32_e32 v187, 1.0, v187
	v_rcp_f32_e32 v156, v156
	v_rcp_f32_e32 v157, v157
	v_rcp_f32_e32 v186, v186
	v_rcp_f32_e32 v187, v187
	v_pk_mul_f32 v[62:63], v[62:63], v[156:157]
	v_pk_mul_f32 v[64:65], v[64:65], v[186:187]
	v_cvt_pk_bf16_f32 v204, v62, v63
	v_cvt_pk_bf16_f32 v205, v64, v65
	global_store_dwordx2 v[238:239], v[204:205], off
	s_waitcnt vmcnt(31)
	v_lshlrev_b32_e32 v156, 16, v206
	v_and_b32_e32 v157, 0xffff0000, v206
	v_lshlrev_b32_e32 v186, 16, v207
	v_and_b32_e32 v187, 0xffff0000, v207
	v_mul_f32_e32 v156, 0xbfb8aa3b, v156
	v_mul_f32_e32 v157, 0xbfb8aa3b, v157
	v_mul_f32_e32 v186, 0xbfb8aa3b, v186
	v_mul_f32_e32 v187, 0xbfb8aa3b, v187
	v_exp_f32_e32 v156, v156
	v_exp_f32_e32 v157, v157
	v_exp_f32_e32 v186, v186
	v_exp_f32_e32 v187, v187
	v_add_f32_e32 v156, 1.0, v156
	v_add_f32_e32 v157, 1.0, v157
	v_add_f32_e32 v186, 1.0, v186
	v_add_f32_e32 v187, 1.0, v187
	v_rcp_f32_e32 v156, v156
	v_rcp_f32_e32 v157, v157
	v_rcp_f32_e32 v186, v186
	v_rcp_f32_e32 v187, v187
	v_pk_mul_f32 v[58:59], v[58:59], v[156:157]
	v_pk_mul_f32 v[60:61], v[60:61], v[186:187]
	v_cvt_pk_bf16_f32 v206, v58, v59
	v_cvt_pk_bf16_f32 v207, v60, v61
	global_store_dwordx2 v[238:239], v[206:207], off offset:32
	s_waitcnt vmcnt(31)
	v_lshlrev_b32_e32 v156, 16, v208
	v_and_b32_e32 v157, 0xffff0000, v208
	v_lshlrev_b32_e32 v186, 16, v209
	v_and_b32_e32 v187, 0xffff0000, v209
	v_mul_f32_e32 v156, 0xbfb8aa3b, v156
	v_mul_f32_e32 v157, 0xbfb8aa3b, v157
	v_mul_f32_e32 v186, 0xbfb8aa3b, v186
	v_mul_f32_e32 v187, 0xbfb8aa3b, v187
	v_exp_f32_e32 v156, v156
	v_exp_f32_e32 v157, v157
	v_exp_f32_e32 v186, v186
	v_exp_f32_e32 v187, v187
	v_add_f32_e32 v156, 1.0, v156
	v_add_f32_e32 v157, 1.0, v157
	v_add_f32_e32 v186, 1.0, v186
	v_add_f32_e32 v187, 1.0, v187
	v_rcp_f32_e32 v156, v156
	v_rcp_f32_e32 v157, v157
	v_rcp_f32_e32 v186, v186
	v_rcp_f32_e32 v187, v187
	v_pk_mul_f32 v[54:55], v[54:55], v[156:157]
	v_pk_mul_f32 v[56:57], v[56:57], v[186:187]
	v_cvt_pk_bf16_f32 v208, v54, v55
	v_cvt_pk_bf16_f32 v209, v56, v57
	global_store_dwordx2 v[238:239], v[208:209], off offset:256
	s_waitcnt vmcnt(31)
	v_lshlrev_b32_e32 v156, 16, v210
	v_and_b32_e32 v157, 0xffff0000, v210
	v_lshlrev_b32_e32 v186, 16, v211
	v_and_b32_e32 v187, 0xffff0000, v211
	v_mul_f32_e32 v156, 0xbfb8aa3b, v156
	v_mul_f32_e32 v157, 0xbfb8aa3b, v157
	v_mul_f32_e32 v186, 0xbfb8aa3b, v186
	v_mul_f32_e32 v187, 0xbfb8aa3b, v187
	v_exp_f32_e32 v156, v156
	v_exp_f32_e32 v157, v157
	v_exp_f32_e32 v186, v186
	v_exp_f32_e32 v187, v187
	v_add_f32_e32 v156, 1.0, v156
	v_add_f32_e32 v157, 1.0, v157
	v_add_f32_e32 v186, 1.0, v186
	v_add_f32_e32 v187, 1.0, v187
	v_rcp_f32_e32 v156, v156
	v_rcp_f32_e32 v157, v157
	v_rcp_f32_e32 v186, v186
	v_rcp_f32_e32 v187, v187
	v_pk_mul_f32 v[50:51], v[50:51], v[156:157]
	v_pk_mul_f32 v[52:53], v[52:53], v[186:187]
	v_cvt_pk_bf16_f32 v210, v50, v51
	v_cvt_pk_bf16_f32 v211, v52, v53
	global_store_dwordx2 v[238:239], v[210:211], off offset:288
	v_lshl_add_u64 v[238:239], v[238:239], 0, s[4:5]
	s_waitcnt vmcnt(31)
	v_lshlrev_b32_e32 v156, 16, v212
	v_and_b32_e32 v157, 0xffff0000, v212
	v_lshlrev_b32_e32 v186, 16, v213
	v_and_b32_e32 v187, 0xffff0000, v213
	v_mul_f32_e32 v156, 0xbfb8aa3b, v156
	v_mul_f32_e32 v157, 0xbfb8aa3b, v157
	v_mul_f32_e32 v186, 0xbfb8aa3b, v186
	v_mul_f32_e32 v187, 0xbfb8aa3b, v187
	v_exp_f32_e32 v156, v156
	v_exp_f32_e32 v157, v157
	v_exp_f32_e32 v186, v186
	v_exp_f32_e32 v187, v187
	v_add_f32_e32 v156, 1.0, v156
	v_add_f32_e32 v157, 1.0, v157
	v_add_f32_e32 v186, 1.0, v186
	v_add_f32_e32 v187, 1.0, v187
	v_rcp_f32_e32 v156, v156
	v_rcp_f32_e32 v157, v157
	v_rcp_f32_e32 v186, v186
	v_rcp_f32_e32 v187, v187
	v_pk_mul_f32 v[46:47], v[46:47], v[156:157]
	v_pk_mul_f32 v[48:49], v[48:49], v[186:187]
	v_cvt_pk_bf16_f32 v212, v46, v47
	v_cvt_pk_bf16_f32 v213, v48, v49
	global_store_dwordx2 v[238:239], v[212:213], off
	s_waitcnt vmcnt(31)
; __device__ __forceinline__ float bflo(unsigned w) { return __uint_as_float(w << 16); }
; __device__ __forceinline__ float bfhi(unsigned w) { return __uint_as_float(w & 0xffff0000u); }
; __device__ __forceinline__ unsigned pk2(float lo, float hi) { f32x2 v = {lo, hi}; bf16x2_t b = __builtin_convertvector(v, bf16x2_t); return __builtin_bit_cast(unsigned, b); }
; __device__ __forceinline__ float sigm(float x) { return __builtin_amdgcn_rcpf(1.f + __expf(-x)); }
;     template <int QPR> __device__ __forceinline__ void tailq(int row, int c, const f32x4 v, int) const { quad(row, c, v); }
;     __device__ __forceinline__ void quad(int row, int c, f32x4 v) const {
;         const u32x2 gw = *(const u32x2*)(Z + (size_t)row * NZ + ZC_MA + c);
;         v[0] *= sigm(bflo(gw.x)); v[1] *= sigm(bfhi(gw.x)); v[2] *= sigm(bflo(gw.y)); v[3] *= sigm(bfhi(gw.y));
;         u32x2 w; w.x = pk2(v[0], v[1]); w.y = pk2(v[2], v[3]); *(u32x2*)(T + (size_t)row * D + c) = w; }
;     template <int QPR> __device__ __forceinline__ void tailq(int row, int c, const f32x4 v, int) const { quad(row, c, v); }
;     __device__ __forceinline__ void operator()(const f32x4 (&acc)[2][2][4][2], const pg8::Unit& u, int wr, int wc, int fr, int fq) const {
;         const int row0 = u.pm * 256 + wr * 64 + fr, col0 = u.pn * 256 + wc * 32 + 4 * fq;
; #pragma unroll
;         for (int ai = 0; ai < 2; ++ai)
; #pragma unroll
;             for (int m = 0; m < 4; ++m) { const int row = row0 + ai * 128 + m * 16;
; #pragma unroll
;                 for (int bj = 0; bj < 2; ++bj)
; #pragma unroll
;                     for (int n = 0; n < 2; ++n) { const int c = col0 + bj * 128 + n * 16;
;                         quad(row, c, acc[ai][bj][m][n]); } }
	v_lshlrev_b32_e32 v156, 16, v214
	v_and_b32_e32 v157, 0xffff0000, v214
	v_lshlrev_b32_e32 v186, 16, v215
	v_and_b32_e32 v187, 0xffff0000, v215
	v_mul_f32_e32 v156, 0xbfb8aa3b, v156
	v_mul_f32_e32 v157, 0xbfb8aa3b, v157
	v_mul_f32_e32 v186, 0xbfb8aa3b, v186
	v_mul_f32_e32 v187, 0xbfb8aa3b, v187
	v_exp_f32_e32 v156, v156
	v_exp_f32_e32 v157, v157
	v_exp_f32_e32 v186, v186
	v_exp_f32_e32 v187, v187
	v_add_f32_e32 v156, 1.0, v156
	v_add_f32_e32 v157, 1.0, v157
	v_add_f32_e32 v186, 1.0, v186
	v_add_f32_e32 v187, 1.0, v187
	v_rcp_f32_e32 v156, v156
	v_rcp_f32_e32 v157, v157
	v_rcp_f32_e32 v186, v186
	v_rcp_f32_e32 v187, v187
	v_pk_mul_f32 v[42:43], v[42:43], v[156:157]
	v_pk_mul_f32 v[44:45], v[44:45], v[186:187]
	v_cvt_pk_bf16_f32 v214, v42, v43
	v_cvt_pk_bf16_f32 v215, v44, v45
	global_store_dwordx2 v[238:239], v[214:215], off offset:32
	s_waitcnt vmcnt(31)
	v_lshlrev_b32_e32 v156, 16, v216
	v_and_b32_e32 v157, 0xffff0000, v216
	v_lshlrev_b32_e32 v186, 16, v217
	v_and_b32_e32 v187, 0xffff0000, v217
	v_mul_f32_e32 v156, 0xbfb8aa3b, v156
	v_mul_f32_e32 v157, 0xbfb8aa3b, v157
	v_mul_f32_e32 v186, 0xbfb8aa3b, v186
	v_mul_f32_e32 v187, 0xbfb8aa3b, v187
	v_exp_f32_e32 v156, v156
	v_exp_f32_e32 v157, v157
	v_exp_f32_e32 v186, v186
	v_exp_f32_e32 v187, v187
	v_add_f32_e32 v156, 1.0, v156
	v_add_f32_e32 v157, 1.0, v157
	v_add_f32_e32 v186, 1.0, v186
	v_add_f32_e32 v187, 1.0, v187
	v_rcp_f32_e32 v156, v156
	v_rcp_f32_e32 v157, v157
	v_rcp_f32_e32 v186, v186
	v_rcp_f32_e32 v187, v187
	v_pk_mul_f32 v[38:39], v[38:39], v[156:157]
	v_pk_mul_f32 v[40:41], v[40:41], v[186:187]
	v_cvt_pk_bf16_f32 v216, v38, v39
	v_cvt_pk_bf16_f32 v217, v40, v41
	global_store_dwordx2 v[238:239], v[216:217], off offset:256
	s_waitcnt vmcnt(31)
	v_lshlrev_b32_e32 v156, 16, v218
	v_and_b32_e32 v157, 0xffff0000, v218
	v_lshlrev_b32_e32 v186, 16, v219
	v_and_b32_e32 v187, 0xffff0000, v219
	v_mul_f32_e32 v156, 0xbfb8aa3b, v156
	v_mul_f32_e32 v157, 0xbfb8aa3b, v157
	v_mul_f32_e32 v186, 0xbfb8aa3b, v186
	v_mul_f32_e32 v187, 0xbfb8aa3b, v187
	v_exp_f32_e32 v156, v156
	v_exp_f32_e32 v157, v157
	v_exp_f32_e32 v186, v186
	v_exp_f32_e32 v187, v187
	v_add_f32_e32 v156, 1.0, v156
	v_add_f32_e32 v157, 1.0, v157
	v_add_f32_e32 v186, 1.0, v186
	v_add_f32_e32 v187, 1.0, v187
	v_rcp_f32_e32 v156, v156
	v_rcp_f32_e32 v157, v157
	v_rcp_f32_e32 v186, v186
	v_rcp_f32_e32 v187, v187
	v_pk_mul_f32 v[34:35], v[34:35], v[156:157]
	v_pk_mul_f32 v[36:37], v[36:37], v[186:187]
	v_cvt_pk_bf16_f32 v218, v34, v35
	v_cvt_pk_bf16_f32 v219, v36, v37
	global_store_dwordx2 v[238:239], v[218:219], off offset:288
	v_lshl_add_u64 v[238:239], v[238:239], 0, s[4:5]
	s_waitcnt vmcnt(31)
	v_lshlrev_b32_e32 v156, 16, v220
	v_and_b32_e32 v157, 0xffff0000, v220
	v_lshlrev_b32_e32 v186, 16, v221
	v_and_b32_e32 v187, 0xffff0000, v221
	v_mul_f32_e32 v156, 0xbfb8aa3b, v156
	v_mul_f32_e32 v157, 0xbfb8aa3b, v157
	v_mul_f32_e32 v186, 0xbfb8aa3b, v186
	v_mul_f32_e32 v187, 0xbfb8aa3b, v187
	v_exp_f32_e32 v156, v156
	v_exp_f32_e32 v157, v157
	v_exp_f32_e32 v186, v186
	v_exp_f32_e32 v187, v187
	v_add_f32_e32 v156, 1.0, v156
	v_add_f32_e32 v157, 1.0, v157
	v_add_f32_e32 v186, 1.0, v186
	v_add_f32_e32 v187, 1.0, v187
	v_rcp_f32_e32 v156, v156
	v_rcp_f32_e32 v157, v157
	v_rcp_f32_e32 v186, v186
	v_rcp_f32_e32 v187, v187
	v_pk_mul_f32 v[30:31], v[30:31], v[156:157]
	v_pk_mul_f32 v[32:33], v[32:33], v[186:187]
	v_cvt_pk_bf16_f32 v220, v30, v31
	v_cvt_pk_bf16_f32 v221, v32, v33
	global_store_dwordx2 v[238:239], v[220:221], off
	s_waitcnt vmcnt(31)
	v_lshlrev_b32_e32 v156, 16, v222
	v_and_b32_e32 v157, 0xffff0000, v222
	v_lshlrev_b32_e32 v186, 16, v223
	v_and_b32_e32 v187, 0xffff0000, v223
	v_mul_f32_e32 v156, 0xbfb8aa3b, v156
	v_mul_f32_e32 v157, 0xbfb8aa3b, v157
	v_mul_f32_e32 v186, 0xbfb8aa3b, v186
	v_mul_f32_e32 v187, 0xbfb8aa3b, v187
	v_exp_f32_e32 v156, v156
	v_exp_f32_e32 v157, v157
	v_exp_f32_e32 v186, v186
	v_exp_f32_e32 v187, v187
	v_add_f32_e32 v156, 1.0, v156
	v_add_f32_e32 v157, 1.0, v157
	v_add_f32_e32 v186, 1.0, v186
	v_add_f32_e32 v187, 1.0, v187
	v_rcp_f32_e32 v156, v156
	v_rcp_f32_e32 v157, v157
	v_rcp_f32_e32 v186, v186
	v_rcp_f32_e32 v187, v187
	v_pk_mul_f32 v[26:27], v[26:27], v[156:157]
	v_pk_mul_f32 v[28:29], v[28:29], v[186:187]
	v_cvt_pk_bf16_f32 v222, v26, v27
	v_cvt_pk_bf16_f32 v223, v28, v29
	global_store_dwordx2 v[238:239], v[222:223], off offset:32
	s_waitcnt vmcnt(31)
	v_lshlrev_b32_e32 v156, 16, v224
	v_and_b32_e32 v157, 0xffff0000, v224
	v_lshlrev_b32_e32 v186, 16, v225
	v_and_b32_e32 v187, 0xffff0000, v225
	v_mul_f32_e32 v156, 0xbfb8aa3b, v156
	v_mul_f32_e32 v157, 0xbfb8aa3b, v157
	v_mul_f32_e32 v186, 0xbfb8aa3b, v186
	v_mul_f32_e32 v187, 0xbfb8aa3b, v187
	v_exp_f32_e32 v156, v156
	v_exp_f32_e32 v157, v157
	v_exp_f32_e32 v186, v186
	v_exp_f32_e32 v187, v187
	v_add_f32_e32 v156, 1.0, v156
	v_add_f32_e32 v157, 1.0, v157
	v_add_f32_e32 v186, 1.0, v186
	v_add_f32_e32 v187, 1.0, v187
	v_rcp_f32_e32 v156, v156
	v_rcp_f32_e32 v157, v157
	v_rcp_f32_e32 v186, v186
	v_rcp_f32_e32 v187, v187
	v_pk_mul_f32 v[22:23], v[22:23], v[156:157]
	v_pk_mul_f32 v[24:25], v[24:25], v[186:187]
	v_cvt_pk_bf16_f32 v224, v22, v23
	v_cvt_pk_bf16_f32 v225, v24, v25
	global_store_dwordx2 v[238:239], v[224:225], off offset:256
	s_waitcnt vmcnt(31)
; __device__ __forceinline__ float bflo(unsigned w) { return __uint_as_float(w << 16); }
; __device__ __forceinline__ float bfhi(unsigned w) { return __uint_as_float(w & 0xffff0000u); }
; __device__ __forceinline__ unsigned pk2(float lo, float hi) { f32x2 v = {lo, hi}; bf16x2_t b = __builtin_convertvector(v, bf16x2_t); return __builtin_bit_cast(unsigned, b); }
; __device__ __forceinline__ float sigm(float x) { return __builtin_amdgcn_rcpf(1.f + __expf(-x)); }
;     template <int QPR> __device__ __forceinline__ void tailq(int row, int c, const f32x4 v, int) const { quad(row, c, v); }
;     __device__ __forceinline__ void quad(int row, int c, f32x4 v) const {
;         const u32x2 gw = *(const u32x2*)(Z + (size_t)row * NZ + ZC_MA + c);
;         v[0] *= sigm(bflo(gw.x)); v[1] *= sigm(bfhi(gw.x)); v[2] *= sigm(bflo(gw.y)); v[3] *= sigm(bfhi(gw.y));
;         u32x2 w; w.x = pk2(v[0], v[1]); w.y = pk2(v[2], v[3]); *(u32x2*)(T + (size_t)row * D + c) = w; }
;     template <int QPR> __device__ __forceinline__ void tailq(int row, int c, const f32x4 v, int) const { quad(row, c, v); }
;     __device__ __forceinline__ void operator()(const f32x4 (&acc)[2][2][4][2], const pg8::Unit& u, int wr, int wc, int fr, int fq) const {
;         const int row0 = u.pm * 256 + wr * 64 + fr, col0 = u.pn * 256 + wc * 32 + 4 * fq;
; #pragma unroll
;         for (int ai = 0; ai < 2; ++ai)
; #pragma unroll
;             for (int m = 0; m < 4; ++m) { const int row = row0 + ai * 128 + m * 16;
; #pragma unroll
;                 for (int bj = 0; bj < 2; ++bj)
; #pragma unroll
;                     for (int n = 0; n < 2; ++n) { const int c = col0 + bj * 128 + n * 16;
;                         quad(row, c, acc[ai][bj][m][n]); } }
	v_lshlrev_b32_e32 v156, 16, v226
	v_and_b32_e32 v157, 0xffff0000, v226
	v_lshlrev_b32_e32 v186, 16, v227
	v_and_b32_e32 v187, 0xffff0000, v227
	v_mul_f32_e32 v156, 0xbfb8aa3b, v156
	v_mul_f32_e32 v157, 0xbfb8aa3b, v157
	v_mul_f32_e32 v186, 0xbfb8aa3b, v186
	v_mul_f32_e32 v187, 0xbfb8aa3b, v187
	v_exp_f32_e32 v156, v156
	v_exp_f32_e32 v157, v157
	v_exp_f32_e32 v186, v186
	v_exp_f32_e32 v187, v187
	v_add_f32_e32 v156, 1.0, v156
	v_add_f32_e32 v157, 1.0, v157
	v_add_f32_e32 v186, 1.0, v186
	v_add_f32_e32 v187, 1.0, v187
	v_rcp_f32_e32 v156, v156
	v_rcp_f32_e32 v157, v157
	v_rcp_f32_e32 v186, v186
	v_rcp_f32_e32 v187, v187
	v_pk_mul_f32 v[18:19], v[18:19], v[156:157]
	v_pk_mul_f32 v[20:21], v[20:21], v[186:187]
	v_cvt_pk_bf16_f32 v226, v18, v19
	v_cvt_pk_bf16_f32 v227, v20, v21
	global_store_dwordx2 v[238:239], v[226:227], off offset:288
	v_lshl_add_u64 v[238:239], v[238:239], 0, s[4:5]
	s_waitcnt vmcnt(31)
	v_lshlrev_b32_e32 v156, 16, v228
	v_and_b32_e32 v157, 0xffff0000, v228
	v_lshlrev_b32_e32 v186, 16, v229
	v_and_b32_e32 v187, 0xffff0000, v229
	v_mul_f32_e32 v156, 0xbfb8aa3b, v156
	v_mul_f32_e32 v157, 0xbfb8aa3b, v157
	v_mul_f32_e32 v186, 0xbfb8aa3b, v186
	v_mul_f32_e32 v187, 0xbfb8aa3b, v187
	v_exp_f32_e32 v156, v156
	v_exp_f32_e32 v157, v157
	v_exp_f32_e32 v186, v186
	v_exp_f32_e32 v187, v187
	v_add_f32_e32 v156, 1.0, v156
	v_add_f32_e32 v157, 1.0, v157
	v_add_f32_e32 v186, 1.0, v186
	v_add_f32_e32 v187, 1.0, v187
	v_rcp_f32_e32 v156, v156
	v_rcp_f32_e32 v157, v157
	v_rcp_f32_e32 v186, v186
	v_rcp_f32_e32 v187, v187
	v_pk_mul_f32 v[14:15], v[14:15], v[156:157]
	v_pk_mul_f32 v[16:17], v[16:17], v[186:187]
	v_cvt_pk_bf16_f32 v228, v14, v15
	v_cvt_pk_bf16_f32 v229, v16, v17
	global_store_dwordx2 v[238:239], v[228:229], off
	s_waitcnt vmcnt(31)
	v_lshlrev_b32_e32 v156, 16, v230
	v_and_b32_e32 v157, 0xffff0000, v230
	v_lshlrev_b32_e32 v186, 16, v231
	v_and_b32_e32 v187, 0xffff0000, v231
	v_mul_f32_e32 v156, 0xbfb8aa3b, v156
	v_mul_f32_e32 v157, 0xbfb8aa3b, v157
	v_mul_f32_e32 v186, 0xbfb8aa3b, v186
	v_mul_f32_e32 v187, 0xbfb8aa3b, v187
	v_exp_f32_e32 v156, v156
	v_exp_f32_e32 v157, v157
	v_exp_f32_e32 v186, v186
	v_exp_f32_e32 v187, v187
	v_add_f32_e32 v156, 1.0, v156
	v_add_f32_e32 v157, 1.0, v157
	v_add_f32_e32 v186, 1.0, v186
	v_add_f32_e32 v187, 1.0, v187
	v_rcp_f32_e32 v156, v156
	v_rcp_f32_e32 v157, v157
	v_rcp_f32_e32 v186, v186
	v_rcp_f32_e32 v187, v187
	v_pk_mul_f32 v[10:11], v[10:11], v[156:157]
	v_pk_mul_f32 v[12:13], v[12:13], v[186:187]
	v_cvt_pk_bf16_f32 v230, v10, v11
	v_cvt_pk_bf16_f32 v231, v12, v13
	global_store_dwordx2 v[238:239], v[230:231], off offset:32
	s_waitcnt vmcnt(31)
	v_lshlrev_b32_e32 v156, 16, v232
	v_and_b32_e32 v157, 0xffff0000, v232
	v_lshlrev_b32_e32 v186, 16, v233
	v_and_b32_e32 v187, 0xffff0000, v233
	v_mul_f32_e32 v156, 0xbfb8aa3b, v156
	v_mul_f32_e32 v157, 0xbfb8aa3b, v157
	v_mul_f32_e32 v186, 0xbfb8aa3b, v186
	v_mul_f32_e32 v187, 0xbfb8aa3b, v187
	v_exp_f32_e32 v156, v156
	v_exp_f32_e32 v157, v157
	v_exp_f32_e32 v186, v186
	v_exp_f32_e32 v187, v187
	v_add_f32_e32 v156, 1.0, v156
	v_add_f32_e32 v157, 1.0, v157
	v_add_f32_e32 v186, 1.0, v186
	v_add_f32_e32 v187, 1.0, v187
	v_rcp_f32_e32 v156, v156
	v_rcp_f32_e32 v157, v157
	v_rcp_f32_e32 v186, v186
	v_rcp_f32_e32 v187, v187
	v_pk_mul_f32 v[6:7], v[6:7], v[156:157]
	v_pk_mul_f32 v[8:9], v[8:9], v[186:187]
	v_cvt_pk_bf16_f32 v232, v6, v7
	v_cvt_pk_bf16_f32 v233, v8, v9
	global_store_dwordx2 v[238:239], v[232:233], off offset:256
	s_waitcnt vmcnt(31)
	v_lshlrev_b32_e32 v156, 16, v234
	v_and_b32_e32 v157, 0xffff0000, v234
	v_lshlrev_b32_e32 v186, 16, v235
	v_and_b32_e32 v187, 0xffff0000, v235
	v_mul_f32_e32 v156, 0xbfb8aa3b, v156
	v_mul_f32_e32 v157, 0xbfb8aa3b, v157
	v_mul_f32_e32 v186, 0xbfb8aa3b, v186
	v_mul_f32_e32 v187, 0xbfb8aa3b, v187
	v_exp_f32_e32 v156, v156
	v_exp_f32_e32 v157, v157
	v_exp_f32_e32 v186, v186
	v_exp_f32_e32 v187, v187
	v_add_f32_e32 v156, 1.0, v156
	v_add_f32_e32 v157, 1.0, v157
	v_add_f32_e32 v186, 1.0, v186
	v_add_f32_e32 v187, 1.0, v187
	v_rcp_f32_e32 v156, v156
	v_rcp_f32_e32 v157, v157
	v_rcp_f32_e32 v186, v186
	v_rcp_f32_e32 v187, v187
	v_pk_mul_f32 v[2:3], v[2:3], v[156:157]
	v_pk_mul_f32 v[4:5], v[4:5], v[186:187]
	v_cvt_pk_bf16_f32 v234, v2, v3
	v_cvt_pk_bf16_f32 v235, v4, v5
	global_store_dwordx2 v[238:239], v[234:235], off offset:288
	s_andn2_b64 vcc, exec, s[38:39]
	s_mov_b64 s[4:5], -1
	s_cbranch_vccnz .LBB0_698
	s_andn2_b64 vcc, exec, s[0:1]
	s_cbranch_vccnz .LBB0_697
	s_barrier
	s_branch .LBB0_697

; #define LAS __attribute__((address_space(3)))
; #define MFMA16(a, b, c) __builtin_amdgcn_mfma_f32_16x16x32_bf16((a), (b), (c), 0, 0, 0)
; template <int MT, int NT, class Epi>
; __device__ __forceinline__ void tail_splitk(LAS unsigned char* lds, const bf16_t* A, const bf16_t* Bt, int K, int row_base, int n_rt, int col_base, int n_ct, int it0, const Epi& E) {
;     ...
;         const bf16_t* ap = A + (size_t)(r0 + fr) * K + fq * 8 + w * nks * 32; const bf16_t* bp = Bt + (size_t)(c0 + fr) * K + fq * 8 + w * nks * 32;
; #pragma unroll 4
;         for (int ks = 0; ks < nks; ++ks) {
;             bf16x8 af[MT], bfv[NT];
; #pragma unroll
;             for (int mt = 0; mt < MT; ++mt) af[mt] = *(const bf16x8*)(ap + (size_t)mt * 16 * K + ks * 32);
; #pragma unroll
;             for (int nt = 0; nt < NT; ++nt) bfv[nt] = *(const bf16x8*)(bp + (size_t)nt * 16 * K + ks * 32);
; #pragma unroll
;             for (int mt = 0; mt < MT; ++mt)
; #pragma unroll
;                 for (int nt = 0; nt < NT; ++nt) acc[mt][nt] = MFMA16(bfv[nt], af[mt], acc[mt][nt]);
;         }
;         LAS float* pw = (LAS float*)(lds + w * WB);
; #pragma unroll
;         for (int mt = 0; mt < MT; ++mt)
; #pragma unroll
;             for (int nt = 0; nt < NT; ++nt) *(LAS f32x4*)(pw + (16 * mt + fr) * RS + 16 * nt + 4 * fq) = acc[mt][nt];
;         __syncthreads();
.LBB0_718:
	s_ashr_i32 s0, s14, 31
	s_lshr_b32 s0, s0, 29
	s_add_i32 s0, s14, s0
	s_and_b32 s1, s0, 0x7fffff8
	s_lshl_b32 s12, s0, 3
	s_sub_i32 s1, s14, s1
	s_andn2_b32 s12, s12, 63
	s_lshl_b32 s15, s1, 5
	v_or_b32_e32 v6, s12, v9
	s_addk_i32 s15, 0x4000
	v_ashrrev_i32_e32 v7, 31, v6
	v_lshlrev_b64 v[6:7], 11, v[6:7]
	v_or_b32_e32 v0, s15, v9
	v_lshl_add_u64 v[66:67], v[4:5], 0, v[6:7]
	v_lshlrev_b64 v[6:7], 11, v[0:1]
	v_lshl_add_u64 v[68:69], v[2:3], 0, v[6:7]
	v_add_co_u32_e64 v6, s[0:1], s64, v68
	global_load_dwordx4 v[76:79], v[66:67], off
	global_load_dwordx4 v[80:83], v[66:67], off offset:64
	v_addc_co_u32_e64 v7, s[0:1], 0, v69, s[0:1]
	v_add_co_u32_e64 v70, s[0:1], s64, v66
	global_load_dwordx4 v[84:87], v[68:69], off
	s_nop 0
	v_addc_co_u32_e64 v71, s[0:1], 0, v67, s[0:1]
	v_add_co_u32_e64 v72, s[0:1], s33, v66
	global_load_dwordx4 v[88:91], v[70:71], off
	s_nop 0
	v_addc_co_u32_e64 v73, s[0:1], 0, v67, s[0:1]
	v_add_co_u32_e64 v74, s[0:1], s6, v66
	global_load_dwordx4 v[92:95], v[72:73], off
	s_nop 0
	v_addc_co_u32_e64 v75, s[0:1], 0, v67, s[0:1]
	global_load_dwordx4 v[96:99], v[74:75], off
	global_load_dwordx4 v[100:103], v[6:7], off
	global_load_dwordx4 v[104:107], v[6:7], off offset:64
	s_nop 0
	s_nop 0
	global_load_dwordx4 v[108:111], v[72:73], off offset:64
	global_load_dwordx4 v[112:115], v[74:75], off offset:64
	s_nop 0
	s_nop 0
	s_nop 0
	global_load_dwordx4 v[116:119], v[68:69], off offset:64
	s_nop 0
	s_nop 0
	s_nop 0
	global_load_dwordx4 v[120:123], v[70:71], off offset:64
	s_nop 0
	s_nop 0
	global_load_dwordx4 v[124:127], v[72:73], off offset:128
	s_nop 0
	s_nop 0
	s_nop 0
	global_load_dwordx4 v[148:151], v[66:67], off offset:128
	s_nop 0
	global_load_dwordx4 v[152:155], v[68:69], off offset:128
	s_nop 0
	global_load_dwordx4 v[164:167], v[6:7], off offset:128
	global_load_dwordx4 v[168:171], v[74:75], off offset:128
	s_nop 0
	s_nop 0
	s_nop 0
	global_load_dwordx4 v[172:175], v[70:71], off offset:128
	s_nop 0
	s_nop 0
	s_nop 0
	global_load_dwordx4 v[176:179], v[72:73], off offset:192
	s_nop 0
	global_load_dwordx4 v[180:183], v[74:75], off offset:192
	s_nop 0
	s_nop 0
	global_load_dwordx4 v[184:187], v[68:69], off offset:192
	s_nop 0
	global_load_dwordx4 v[204:207], v[66:67], off offset:192
	global_load_dwordx4 v[208:211], v[70:71], off offset:192
	s_nop 0
	s_nop 0
	s_nop 0
	global_load_dwordx4 v[212:215], v[6:7], off offset:192
	s_nop 4
	s_nop 0
	s_nop 0
	s_nop 0
	s_nop 5
	s_nop 0
	s_nop 0
	s_nop 0
	s_nop 7
	s_nop 0
	s_waitcnt vmcnt(0)
	s_nop 0
	s_nop 0
	s_nop 0
	v_mfma_f32_16x16x32_bf16 v[30:33], v[76:79], v[84:87], 0
	s_nop 0
	s_nop 0
	v_mfma_f32_16x16x32_bf16 v[14:17], v[76:79], v[100:103], 0
	v_mfma_f32_16x16x32_bf16 v[38:41], v[88:91], v[84:87], 0
	v_mfma_f32_16x16x32_bf16 v[42:45], v[92:95], v[84:87], 0
	v_mfma_f32_16x16x32_bf16 v[18:21], v[96:99], v[84:87], 0
	v_mfma_f32_16x16x32_bf16 v[26:29], v[88:91], v[100:103], 0
	v_mfma_f32_16x16x32_bf16 v[34:37], v[92:95], v[100:103], 0
	v_mfma_f32_16x16x32_bf16 v[22:25], v[96:99], v[100:103], 0
	s_nop 0
	s_nop 0
	v_mfma_f32_16x16x32_bf16 v[30:33], v[80:83], v[116:119], v[30:33]
	v_mfma_f32_16x16x32_bf16 v[14:17], v[80:83], v[104:107], v[14:17]
	s_nop 0
	v_mfma_f32_16x16x32_bf16 v[42:45], v[108:111], v[116:119], v[42:45]
	v_mfma_f32_16x16x32_bf16 v[34:37], v[108:111], v[104:107], v[34:37]
	s_nop 0
	s_nop 0
	v_mfma_f32_16x16x32_bf16 v[38:41], v[120:123], v[116:119], v[38:41]
	v_mfma_f32_16x16x32_bf16 v[18:21], v[112:115], v[116:119], v[18:21]
	s_nop 0
	v_mfma_f32_16x16x32_bf16 v[26:29], v[120:123], v[104:107], v[26:29]
	s_nop 0
	v_mfma_f32_16x16x32_bf16 v[22:25], v[112:115], v[104:107], v[22:25]
	s_nop 0
	s_nop 0
	s_nop 0
	v_mfma_f32_16x16x32_bf16 v[30:33], v[148:151], v[152:155], v[30:33]
	v_mfma_f32_16x16x32_bf16 v[14:17], v[148:151], v[164:167], v[14:17]
	s_nop 0
	v_mfma_f32_16x16x32_bf16 v[42:45], v[124:127], v[152:155], v[42:45]
	v_mfma_f32_16x16x32_bf16 v[18:21], v[168:171], v[152:155], v[18:21]
	v_mfma_f32_16x16x32_bf16 v[34:37], v[124:127], v[164:167], v[34:37]
	s_nop 0
	v_mfma_f32_16x16x32_bf16 v[22:25], v[168:171], v[164:167], v[22:25]
	s_nop 0
	s_nop 0
	v_mfma_f32_16x16x32_bf16 v[38:41], v[172:175], v[152:155], v[38:41]
	s_nop 0
	v_mfma_f32_16x16x32_bf16 v[26:29], v[172:175], v[164:167], v[26:29]
	s_nop 0
	s_nop 0
	s_nop 0
	v_mfma_f32_16x16x32_bf16 v[42:45], v[176:179], v[184:187], v[42:45]
	v_mfma_f32_16x16x32_bf16 v[30:33], v[204:207], v[184:187], v[30:33]
	v_mfma_f32_16x16x32_bf16 v[38:41], v[208:211], v[184:187], v[38:41]
	v_mfma_f32_16x16x32_bf16 v[18:21], v[180:183], v[184:187], v[18:21]
	s_nop 0
	s_nop 4
	ds_write_b128 v12, v[30:33]
	ds_write_b128 v12, v[38:41] offset:64
	ds_write_b128 v12, v[42:45] offset:128
	ds_write_b128 v12, v[18:21] offset:192
	s_nop 0
	v_mfma_f32_16x16x32_bf16 v[14:17], v[204:207], v[212:215], v[14:17]
	v_mfma_f32_16x16x32_bf16 v[26:29], v[208:211], v[212:215], v[26:29]
	v_mfma_f32_16x16x32_bf16 v[18:21], v[176:179], v[212:215], v[34:37]
	s_nop 5
	ds_write_b128 v12, v[14:17] offset:4352
	ds_write_b128 v12, v[26:29] offset:4416
	ds_write_b128 v12, v[18:21] offset:4480
	v_mfma_f32_16x16x32_bf16 v[14:17], v[180:183], v[212:215], v[22:25]
	s_nop 7
	ds_write_b128 v12, v[14:17] offset:4544
	s_waitcnt lgkmcnt(0)
	s_barrier
	s_and_saveexec_b64 s[4:5], vcc
	s_cbranch_execz .LBB0_717
	v_add_u32_e32 v0, s12, v10
	s_mov_b64 s[12:13], 0
	v_mov_b32_e32 v6, v11
	v_mov_b32_e32 v7, v8

; #define LAS __attribute__((address_space(3)))
; #define MFMA16(a, b, c) __builtin_amdgcn_mfma_f32_16x16x32_bf16((a), (b), (c), 0, 0, 0)
; template <int MT, int NT, class Epi>
; __device__ __forceinline__ void tail_splitk(LAS unsigned char* lds, const bf16_t* A, const bf16_t* Bt, int K, int row_base, int n_rt, int col_base, int n_ct, int it0, const Epi& E) {
;     ...
;         const bf16_t* ap = A + (size_t)(r0 + fr) * K + fq * 8 + w * nks * 32; const bf16_t* bp = Bt + (size_t)(c0 + fr) * K + fq * 8 + w * nks * 32;
; #pragma unroll 4
;         for (int ks = 0; ks < nks; ++ks) {
;             bf16x8 af[MT], bfv[NT];
; #pragma unroll
;             for (int mt = 0; mt < MT; ++mt) af[mt] = *(const bf16x8*)(ap + (size_t)mt * 16 * K + ks * 32);
; #pragma unroll
;             for (int nt = 0; nt < NT; ++nt) bfv[nt] = *(const bf16x8*)(bp + (size_t)nt * 16 * K + ks * 32);
; #pragma unroll
;             for (int mt = 0; mt < MT; ++mt)
; #pragma unroll
;                 for (int nt = 0; nt < NT; ++nt) acc[mt][nt] = MFMA16(bfv[nt], af[mt], acc[mt][nt]);
;         }
;         LAS float* pw = (LAS float*)(lds + w * WB);
; #pragma unroll
;         for (int mt = 0; mt < MT; ++mt)
; #pragma unroll
;             for (int nt = 0; nt < NT; ++nt) *(LAS f32x4*)(pw + (16 * mt + fr) * RS + 16 * nt + 4 * fq) = acc[mt][nt];
;         __syncthreads();
.LBB0_802:
	s_ashr_i32 s0, s14, 31
	s_lshr_b32 s0, s0, 29
	s_add_i32 s0, s14, s0
	s_and_b32 s1, s0, 0x7fffff8
	s_lshl_b32 s12, s0, 3
	s_sub_i32 s1, s14, s1
	s_andn2_b32 s12, s12, 63
	s_lshl_b32 s15, s1, 5
	v_or_b32_e32 v6, s12, v9
	s_addk_i32 s15, 0x4000
	v_ashrrev_i32_e32 v7, 31, v6
	v_lshlrev_b64 v[6:7], 11, v[6:7]
	v_or_b32_e32 v0, s15, v9
	v_lshl_add_u64 v[66:67], v[4:5], 0, v[6:7]
	v_lshlrev_b64 v[6:7], 11, v[0:1]
	v_lshl_add_u64 v[68:69], v[2:3], 0, v[6:7]
	v_add_co_u32_e64 v6, s[0:1], s64, v68
	global_load_dwordx4 v[76:79], v[66:67], off
	global_load_dwordx4 v[80:83], v[66:67], off offset:64
	v_addc_co_u32_e64 v7, s[0:1], 0, v69, s[0:1]
	v_add_co_u32_e64 v70, s[0:1], s64, v66
	global_load_dwordx4 v[84:87], v[68:69], off
	s_nop 0
	v_addc_co_u32_e64 v71, s[0:1], 0, v67, s[0:1]
	v_add_co_u32_e64 v72, s[0:1], s33, v66
	global_load_dwordx4 v[88:91], v[70:71], off
	s_nop 0
	v_addc_co_u32_e64 v73, s[0:1], 0, v67, s[0:1]
	v_add_co_u32_e64 v74, s[0:1], s6, v66
	global_load_dwordx4 v[92:95], v[72:73], off
	s_nop 0
	v_addc_co_u32_e64 v75, s[0:1], 0, v67, s[0:1]
	global_load_dwordx4 v[96:99], v[74:75], off
	global_load_dwordx4 v[100:103], v[6:7], off
	global_load_dwordx4 v[104:107], v[6:7], off offset:64
	s_nop 0
	s_nop 0
	global_load_dwordx4 v[108:111], v[72:73], off offset:64
	global_load_dwordx4 v[112:115], v[74:75], off offset:64
	s_nop 0
	s_nop 0
	s_nop 0
	global_load_dwordx4 v[116:119], v[68:69], off offset:64
	s_nop 0
	s_nop 0
	s_nop 0
	global_load_dwordx4 v[120:123], v[70:71], off offset:64
	s_nop 0
	s_nop 0
	global_load_dwordx4 v[124:127], v[72:73], off offset:128
	s_nop 0
	s_nop 0
	s_nop 0
	global_load_dwordx4 v[148:151], v[66:67], off offset:128
	s_nop 0
	global_load_dwordx4 v[152:155], v[68:69], off offset:128
	s_nop 0
	global_load_dwordx4 v[164:167], v[6:7], off offset:128
	global_load_dwordx4 v[168:171], v[74:75], off offset:128
	s_nop 0
	s_nop 0
	s_nop 0
	global_load_dwordx4 v[172:175], v[70:71], off offset:128
	s_nop 0
	s_nop 0
	s_nop 0
	global_load_dwordx4 v[176:179], v[72:73], off offset:192
	s_nop 0
	global_load_dwordx4 v[180:183], v[74:75], off offset:192
	s_nop 0
	s_nop 0
	global_load_dwordx4 v[184:187], v[68:69], off offset:192
	s_nop 0
	global_load_dwordx4 v[204:207], v[66:67], off offset:192
	global_load_dwordx4 v[208:211], v[70:71], off offset:192
	s_nop 0
	s_nop 0
	s_nop 0
	global_load_dwordx4 v[212:215], v[6:7], off offset:192
	s_nop 4
	s_nop 0
	s_nop 0
	s_nop 0
	s_nop 5
	s_nop 0
	s_nop 0
	s_nop 0
	s_nop 7
	s_nop 0
	s_waitcnt vmcnt(0)
	s_nop 0
	s_nop 0
	s_nop 0
	v_mfma_f32_16x16x32_bf16 v[30:33], v[76:79], v[84:87], 0
	s_nop 0
	s_nop 0
	v_mfma_f32_16x16x32_bf16 v[14:17], v[76:79], v[100:103], 0
	v_mfma_f32_16x16x32_bf16 v[38:41], v[88:91], v[84:87], 0
	v_mfma_f32_16x16x32_bf16 v[42:45], v[92:95], v[84:87], 0
	v_mfma_f32_16x16x32_bf16 v[18:21], v[96:99], v[84:87], 0
	v_mfma_f32_16x16x32_bf16 v[26:29], v[88:91], v[100:103], 0
	v_mfma_f32_16x16x32_bf16 v[34:37], v[92:95], v[100:103], 0
	v_mfma_f32_16x16x32_bf16 v[22:25], v[96:99], v[100:103], 0
	s_nop 0
	s_nop 0
	v_mfma_f32_16x16x32_bf16 v[30:33], v[80:83], v[116:119], v[30:33]
	v_mfma_f32_16x16x32_bf16 v[14:17], v[80:83], v[104:107], v[14:17]
	s_nop 0
	v_mfma_f32_16x16x32_bf16 v[42:45], v[108:111], v[116:119], v[42:45]
	v_mfma_f32_16x16x32_bf16 v[34:37], v[108:111], v[104:107], v[34:37]
	s_nop 0
	s_nop 0
	v_mfma_f32_16x16x32_bf16 v[38:41], v[120:123], v[116:119], v[38:41]
	v_mfma_f32_16x16x32_bf16 v[18:21], v[112:115], v[116:119], v[18:21]
	s_nop 0
	v_mfma_f32_16x16x32_bf16 v[26:29], v[120:123], v[104:107], v[26:29]
	s_nop 0
	v_mfma_f32_16x16x32_bf16 v[22:25], v[112:115], v[104:107], v[22:25]
	s_nop 0
	s_nop 0
	s_nop 0
	v_mfma_f32_16x16x32_bf16 v[30:33], v[148:151], v[152:155], v[30:33]
	v_mfma_f32_16x16x32_bf16 v[14:17], v[148:151], v[164:167], v[14:17]
	s_nop 0
	v_mfma_f32_16x16x32_bf16 v[42:45], v[124:127], v[152:155], v[42:45]
	v_mfma_f32_16x16x32_bf16 v[18:21], v[168:171], v[152:155], v[18:21]
	v_mfma_f32_16x16x32_bf16 v[34:37], v[124:127], v[164:167], v[34:37]
	s_nop 0
	v_mfma_f32_16x16x32_bf16 v[22:25], v[168:171], v[164:167], v[22:25]
	s_nop 0
	s_nop 0
	v_mfma_f32_16x16x32_bf16 v[38:41], v[172:175], v[152:155], v[38:41]
	s_nop 0
	v_mfma_f32_16x16x32_bf16 v[26:29], v[172:175], v[164:167], v[26:29]
	s_nop 0
	s_nop 0
	s_nop 0
	v_mfma_f32_16x16x32_bf16 v[42:45], v[176:179], v[184:187], v[42:45]
	v_mfma_f32_16x16x32_bf16 v[30:33], v[204:207], v[184:187], v[30:33]
	v_mfma_f32_16x16x32_bf16 v[38:41], v[208:211], v[184:187], v[38:41]
	v_mfma_f32_16x16x32_bf16 v[18:21], v[180:183], v[184:187], v[18:21]
	s_nop 0
	s_nop 4
	ds_write_b128 v12, v[30:33]
	ds_write_b128 v12, v[38:41] offset:64
	ds_write_b128 v12, v[42:45] offset:128
	ds_write_b128 v12, v[18:21] offset:192
	s_nop 0
	v_mfma_f32_16x16x32_bf16 v[14:17], v[204:207], v[212:215], v[14:17]
	v_mfma_f32_16x16x32_bf16 v[26:29], v[208:211], v[212:215], v[26:29]
	v_mfma_f32_16x16x32_bf16 v[18:21], v[176:179], v[212:215], v[34:37]
	s_nop 5
	ds_write_b128 v12, v[14:17] offset:4352
	ds_write_b128 v12, v[26:29] offset:4416
	ds_write_b128 v12, v[18:21] offset:4480
	v_mfma_f32_16x16x32_bf16 v[14:17], v[180:183], v[212:215], v[22:25]
	s_nop 7
	ds_write_b128 v12, v[14:17] offset:4544
	s_waitcnt lgkmcnt(0)
	s_barrier
	s_and_saveexec_b64 s[4:5], vcc
	s_cbranch_execz .LBB0_801
	v_add_u32_e32 v0, s12, v10
	s_mov_b64 s[12:13], 0
	v_mov_b32_e32 v13, v11
	v_mov_b32_e32 v14, v8

; #define LAS __attribute__((address_space(3)))
; #define MFMA16(a, b, c) __builtin_amdgcn_mfma_f32_16x16x32_bf16((a), (b), (c), 0, 0, 0)
;     template <int QPR> __device__ __forceinline__ void tailq(int row, int c, const f32x4 v, int) const { quad(row, c, v); }
;     template <int QPR> __device__ __forceinline__ void tailq(int row, int c, const f32x4 v, int) const { quad(row, c, v); }
;     template <int QPR> __device__ __forceinline__ void tailq(int row, int c, const f32x4 v, int c0) const {
;         float sq = quad(row, c, v);
; #pragma unroll
;         for (int o = 1; o < QPR; o <<= 1) sq += __shfl_xor(sq, o);
;         if ((threadIdx.x & (QPR - 1)) == 0) ss[(size_t)row * 16 + (c0 >> 6)] = sq; }
; template <int MT, int NT, class Epi>
; __device__ __forceinline__ void tail_splitk(LAS unsigned char* lds, const bf16_t* A, const bf16_t* Bt, int K, int row_base, int n_rt, int col_base, int n_ct, int it0, const Epi& E) {
;     ...
;         const bf16_t* ap = A + (size_t)(r0 + fr) * K + fq * 8 + w * nks * 32; const bf16_t* bp = Bt + (size_t)(c0 + fr) * K + fq * 8 + w * nks * 32;
; #pragma unroll 4
;         for (int ks = 0; ks < nks; ++ks) {
;             bf16x8 af[MT], bfv[NT];
; #pragma unroll
;             for (int mt = 0; mt < MT; ++mt) af[mt] = *(const bf16x8*)(ap + (size_t)mt * 16 * K + ks * 32);
; #pragma unroll
;             for (int nt = 0; nt < NT; ++nt) bfv[nt] = *(const bf16x8*)(bp + (size_t)nt * 16 * K + ks * 32);
; #pragma unroll
;             for (int mt = 0; mt < MT; ++mt)
; #pragma unroll
;                 for (int nt = 0; nt < NT; ++nt) acc[mt][nt] = MFMA16(bfv[nt], af[mt], acc[mt][nt]);
;         }
;         LAS float* pw = (LAS float*)(lds + w * WB);
; #pragma unroll
;         for (int mt = 0; mt < MT; ++mt)
; #pragma unroll
;             for (int nt = 0; nt < NT; ++nt) *(LAS f32x4*)(pw + (16 * mt + fr) * RS + 16 * nt + 4 * fq) = acc[mt][nt];
;         __syncthreads();
.LBB0_906:
	s_ashr_i32 s0, s30, 31
	s_lshr_b32 s0, s0, 29
	s_add_i32 s0, s30, s0
	s_ashr_i32 s38, s0, 3
	s_and_b32 s0, s0, 0x7fffff8
	s_sub_i32 s0, s30, s0
	s_lshl_b32 s40, s38, 6
	s_lshl_b32 s43, s0, 5
	v_or_b32_e32 v6, s40, v9
	s_addk_i32 s43, 0x4000
	v_ashrrev_i32_e32 v7, 31, v6
	v_lshlrev_b64 v[6:7], 11, v[6:7]
	v_or_b32_e32 v0, s43, v9
	v_lshl_add_u64 v[66:67], v[4:5], 0, v[6:7]
	v_lshlrev_b64 v[6:7], 11, v[0:1]
	v_lshl_add_u64 v[68:69], v[2:3], 0, v[6:7]
	v_add_co_u32_e64 v6, s[0:1], s64, v68
	global_load_dwordx4 v[76:79], v[66:67], off
	global_load_dwordx4 v[80:83], v[66:67], off offset:64
	v_addc_co_u32_e64 v7, s[0:1], 0, v69, s[0:1]
	v_add_co_u32_e64 v70, s[0:1], s64, v66
	global_load_dwordx4 v[84:87], v[68:69], off
	s_nop 0
	v_addc_co_u32_e64 v71, s[0:1], 0, v67, s[0:1]
	v_add_co_u32_e64 v72, s[0:1], s33, v66
	global_load_dwordx4 v[88:91], v[70:71], off
	s_nop 0
	v_addc_co_u32_e64 v73, s[0:1], 0, v67, s[0:1]
	v_add_co_u32_e64 v74, s[0:1], s6, v66
	global_load_dwordx4 v[92:95], v[72:73], off
	s_nop 0
	v_addc_co_u32_e64 v75, s[0:1], 0, v67, s[0:1]
	global_load_dwordx4 v[96:99], v[74:75], off
	global_load_dwordx4 v[100:103], v[6:7], off
	global_load_dwordx4 v[104:107], v[6:7], off offset:64
	s_nop 0
	s_nop 0
	global_load_dwordx4 v[108:111], v[72:73], off offset:64
	global_load_dwordx4 v[112:115], v[74:75], off offset:64
	s_nop 0
	s_nop 0
	s_nop 0
	global_load_dwordx4 v[116:119], v[68:69], off offset:64
	s_nop 0
	s_nop 0
	s_nop 0
	global_load_dwordx4 v[120:123], v[70:71], off offset:64
	s_nop 0
	s_nop 0
	global_load_dwordx4 v[124:127], v[72:73], off offset:128
	s_nop 0
	s_nop 0
	s_nop 0
	global_load_dwordx4 v[148:151], v[66:67], off offset:128
	s_nop 0
	global_load_dwordx4 v[152:155], v[68:69], off offset:128
	s_nop 0
	global_load_dwordx4 v[164:167], v[6:7], off offset:128
	global_load_dwordx4 v[168:171], v[74:75], off offset:128
	s_nop 0
	s_nop 0
	s_nop 0
	global_load_dwordx4 v[172:175], v[70:71], off offset:128
	s_nop 0
	s_nop 0
	s_nop 0
	global_load_dwordx4 v[176:179], v[72:73], off offset:192
	s_nop 0
	global_load_dwordx4 v[180:183], v[74:75], off offset:192
	s_nop 0
	s_nop 0
	global_load_dwordx4 v[184:187], v[68:69], off offset:192
	s_nop 0
	global_load_dwordx4 v[204:207], v[66:67], off offset:192
	global_load_dwordx4 v[208:211], v[70:71], off offset:192
	s_nop 0
	s_nop 0
	s_nop 0
	global_load_dwordx4 v[212:215], v[6:7], off offset:192
	s_nop 4
	s_nop 0
	s_nop 0
	s_nop 0
	s_nop 5
	s_nop 0
	s_nop 0
	s_nop 0
	s_nop 7
	s_nop 0
	s_waitcnt vmcnt(0)
	s_nop 0
	s_nop 0
	s_nop 0
	v_mfma_f32_16x16x32_bf16 v[30:33], v[76:79], v[84:87], 0
	s_nop 0
	s_nop 0
	v_mfma_f32_16x16x32_bf16 v[14:17], v[76:79], v[100:103], 0
	v_mfma_f32_16x16x32_bf16 v[38:41], v[88:91], v[84:87], 0
	v_mfma_f32_16x16x32_bf16 v[42:45], v[92:95], v[84:87], 0
	v_mfma_f32_16x16x32_bf16 v[18:21], v[96:99], v[84:87], 0
	v_mfma_f32_16x16x32_bf16 v[26:29], v[88:91], v[100:103], 0
	v_mfma_f32_16x16x32_bf16 v[34:37], v[92:95], v[100:103], 0
	v_mfma_f32_16x16x32_bf16 v[22:25], v[96:99], v[100:103], 0
	s_nop 0
	s_nop 0
	v_mfma_f32_16x16x32_bf16 v[30:33], v[80:83], v[116:119], v[30:33]
	v_mfma_f32_16x16x32_bf16 v[14:17], v[80:83], v[104:107], v[14:17]
	s_nop 0
	v_mfma_f32_16x16x32_bf16 v[42:45], v[108:111], v[116:119], v[42:45]
	v_mfma_f32_16x16x32_bf16 v[34:37], v[108:111], v[104:107], v[34:37]
	s_nop 0
	s_nop 0
	v_mfma_f32_16x16x32_bf16 v[38:41], v[120:123], v[116:119], v[38:41]
	v_mfma_f32_16x16x32_bf16 v[18:21], v[112:115], v[116:119], v[18:21]
	s_nop 0
	v_mfma_f32_16x16x32_bf16 v[26:29], v[120:123], v[104:107], v[26:29]
	s_nop 0
	v_mfma_f32_16x16x32_bf16 v[22:25], v[112:115], v[104:107], v[22:25]
	s_nop 0
	s_nop 0
	s_nop 0
	v_mfma_f32_16x16x32_bf16 v[30:33], v[148:151], v[152:155], v[30:33]
	v_mfma_f32_16x16x32_bf16 v[14:17], v[148:151], v[164:167], v[14:17]
	s_nop 0
	v_mfma_f32_16x16x32_bf16 v[42:45], v[124:127], v[152:155], v[42:45]
	v_mfma_f32_16x16x32_bf16 v[18:21], v[168:171], v[152:155], v[18:21]
	v_mfma_f32_16x16x32_bf16 v[34:37], v[124:127], v[164:167], v[34:37]
	s_nop 0
	v_mfma_f32_16x16x32_bf16 v[22:25], v[168:171], v[164:167], v[22:25]
	s_nop 0
	s_nop 0
	v_mfma_f32_16x16x32_bf16 v[38:41], v[172:175], v[152:155], v[38:41]
	s_nop 0
	v_mfma_f32_16x16x32_bf16 v[26:29], v[172:175], v[164:167], v[26:29]
	s_nop 0
	s_nop 0
	s_nop 0
	v_mfma_f32_16x16x32_bf16 v[42:45], v[176:179], v[184:187], v[42:45]
	v_mfma_f32_16x16x32_bf16 v[30:33], v[204:207], v[184:187], v[30:33]
	v_mfma_f32_16x16x32_bf16 v[38:41], v[208:211], v[184:187], v[38:41]
	v_mfma_f32_16x16x32_bf16 v[18:21], v[180:183], v[184:187], v[18:21]
	s_nop 0
	s_nop 4
	ds_write_b128 v12, v[30:33]
	ds_write_b128 v12, v[38:41] offset:64
	ds_write_b128 v12, v[42:45] offset:128
	ds_write_b128 v12, v[18:21] offset:192
	s_nop 0
	v_mfma_f32_16x16x32_bf16 v[14:17], v[204:207], v[212:215], v[14:17]
	v_mfma_f32_16x16x32_bf16 v[26:29], v[208:211], v[212:215], v[26:29]
	v_mfma_f32_16x16x32_bf16 v[18:21], v[176:179], v[212:215], v[34:37]
	s_nop 5
	ds_write_b128 v12, v[14:17] offset:4352
	ds_write_b128 v12, v[26:29] offset:4416
	ds_write_b128 v12, v[18:21] offset:4480
	v_mfma_f32_16x16x32_bf16 v[14:17], v[180:183], v[212:215], v[22:25]
	s_nop 7
	ds_write_b128 v12, v[14:17] offset:4544
	s_waitcnt lgkmcnt(0)
	s_barrier
	s_and_saveexec_b64 s[4:5], vcc
	s_cbranch_execz .LBB0_905
	v_and_b32_e32 v0, 64, v203
	v_add_u32_e32 v6, 64, v0
	v_xor_b32_e32 v0, 1, v203
	v_cmp_lt_i32_e64 s[0:1], v0, v6
	v_xor_b32_e32 v7, 2, v203
	s_ashr_i32 s39, s38, 31
	v_cndmask_b32_e64 v0, v203, v0, s[0:1]
	v_cmp_lt_i32_e64 s[0:1], v7, v6
	v_lshlrev_b32_e32 v0, 2, v0
	v_add_u32_e32 v16, s40, v10
	v_cndmask_b32_e64 v7, v203, v7, s[0:1]
	v_lshlrev_b32_e32 v13, 2, v7
	v_xor_b32_e32 v7, 4, v203
	v_cmp_lt_i32_e64 s[0:1], v7, v6
	s_mov_b64 s[40:41], 0
	v_mov_b32_e32 v17, v11
	v_cndmask_b32_e64 v7, v203, v7, s[0:1]
	v_lshlrev_b32_e32 v14, 2, v7
	v_xor_b32_e32 v7, 8, v203
	v_cmp_lt_i32_e64 s[0:1], v7, v6
	v_mov_b32_e32 v18, v8
	s_nop 0
	v_cndmask_b32_e64 v6, v203, v7, s[0:1]
	s_lshl_b64 s[0:1], s[38:39], 2
	s_add_u32 s38, s22, s0
	v_lshlrev_b32_e32 v15, 2, v6
	s_addc_u32 s39, s23, s1
	s_branch .LBB0_909

; #define MFMA16(a, b, c) __builtin_amdgcn_mfma_f32_16x16x32_bf16((a), (b), (c), 0, 0, 0)
; template <int MT, int NT, class Epi>
; __device__ __forceinline__ void tail_splitk(LAS unsigned char* lds, const bf16_t* A, const bf16_t* Bt, int K, int row_base, int n_rt, int col_base, int n_ct, int it0, const Epi& E) {
;     ...
;         const bf16_t* ap = A + (size_t)(r0 + fr) * K + fq * 8 + w * nks * 32; const bf16_t* bp = Bt + (size_t)(c0 + fr) * K + fq * 8 + w * nks * 32;
; #pragma unroll 4
;         for (int ks = 0; ks < nks; ++ks) {
;             bf16x8 af[MT], bfv[NT];
; #pragma unroll
;             for (int mt = 0; mt < MT; ++mt) af[mt] = *(const bf16x8*)(ap + (size_t)mt * 16 * K + ks * 32);
; #pragma unroll
;             for (int nt = 0; nt < NT; ++nt) bfv[nt] = *(const bf16x8*)(bp + (size_t)nt * 16 * K + ks * 32);
; #pragma unroll
;             for (int mt = 0; mt < MT; ++mt)
; #pragma unroll
;                 for (int nt = 0; nt < NT; ++nt) acc[mt][nt] = MFMA16(bfv[nt], af[mt], acc[mt][nt]);
;         }
.LBB0_992:
	s_ashr_i32 s0, s41, 31
	s_lshr_b32 s0, s0, 30
	s_add_i32 s0, s41, s0
	s_and_b32 s1, s0, 0x3fffffc
	s_sub_i32 s1, s41, s1
	s_lshl_b32 s52, s1, 6
	s_addk_i32 s52, 0x4000
	v_or_b32_e32 v0, s52, v99
	v_lshlrev_b64 v[2:3], 11, v[0:1]
	s_waitcnt vmcnt(0)
	v_lshl_add_u64 v[84:85], v[78:79], 0, v[2:3]
	s_lshl_b32 s38, s0, 4
	v_add_co_u32_e64 v86, s[0:1], s64, v84
	s_andn2_b32 s38, s38, 63
	s_nop 0
	v_addc_co_u32_e64 v87, s[0:1], 0, v85, s[0:1]
	v_or_b32_e32 v2, s38, v99
	v_add_co_u32_e64 v88, s[0:1], s33, v84
	v_ashrrev_i32_e32 v3, 31, v2
	s_nop 0
	v_addc_co_u32_e64 v89, s[0:1], 0, v85, s[0:1]
	v_lshlrev_b64 v[2:3], 11, v[2:3]
	v_add_co_u32_e64 v90, s[0:1], s6, v84
	v_lshl_add_u64 v[82:83], v[80:81], 0, v[2:3]
	s_nop 0
	v_addc_co_u32_e64 v91, s[0:1], 0, v85, s[0:1]
	v_add_co_u32_e64 v94, s[0:1], s64, v82
	global_load_dwordx4 v[124:127], v[84:85], off
	global_load_dwordx4 v[148:151], v[86:87], off
	v_addc_co_u32_e64 v95, s[0:1], 0, v83, s[0:1]
	v_add_co_u32_e64 v96, s[0:1], s33, v82
	global_load_dwordx4 v[152:155], v[88:89], off
	s_nop 0
	v_addc_co_u32_e64 v97, s[0:1], 0, v83, s[0:1]
	v_add_co_u32_e64 v92, s[0:1], s6, v82
	global_load_dwordx4 v[164:167], v[90:91], off
	global_load_dwordx4 v[168:171], v[82:83], off
	v_addc_co_u32_e64 v93, s[0:1], 0, v83, s[0:1]
	global_load_dwordx4 v[172:175], v[94:95], off
	global_load_dwordx4 v[176:179], v[92:93], off
	global_load_dwordx4 v[180:183], v[96:97], off
	s_nop 0
	s_nop 0
	s_nop 0
	global_load_dwordx4 v[184:187], v[84:85], off offset:64
	global_load_dwordx4 v[204:207], v[86:87], off offset:64
	global_load_dwordx4 v[208:211], v[88:89], off offset:64
	global_load_dwordx4 v[212:215], v[90:91], off offset:64
	global_load_dwordx4 v[216:219], v[82:83], off offset:64
	global_load_dwordx4 v[220:223], v[94:95], off offset:64
	global_load_dwordx4 v[224:227], v[96:97], off offset:64
	global_load_dwordx4 v[228:231], v[92:93], off offset:64
	s_nop 0
	s_nop 0
	s_nop 0
	global_load_dwordx4 v[232:235], v[84:85], off offset:128
	global_load_dwordx4 v[236:239], v[86:87], off offset:128
	s_waitcnt vmcnt(0)
	s_nop 0
	s_nop 0
	s_nop 0
	v_mfma_f32_16x16x32_bf16 v[62:65], v[168:171], v[124:127], 0
	v_mfma_f32_16x16x32_bf16 v[66:69], v[172:175], v[124:127], 0
	v_mfma_f32_16x16x32_bf16 v[70:73], v[180:183], v[124:127], 0
	v_mfma_f32_16x16x32_bf16 v[74:77], v[176:179], v[124:127], 0
	v_mfma_f32_16x16x32_bf16 v[54:57], v[168:171], v[148:151], 0
	v_mfma_f32_16x16x32_bf16 v[42:45], v[172:175], v[148:151], 0
	v_mfma_f32_16x16x32_bf16 v[46:49], v[180:183], v[148:151], 0
	v_mfma_f32_16x16x32_bf16 v[50:53], v[176:179], v[148:151], 0
	v_mfma_f32_16x16x32_bf16 v[38:41], v[168:171], v[152:155], 0
	v_mfma_f32_16x16x32_bf16 v[18:21], v[172:175], v[152:155], 0
	v_mfma_f32_16x16x32_bf16 v[22:25], v[180:183], v[152:155], 0
	v_mfma_f32_16x16x32_bf16 v[26:29], v[176:179], v[152:155], 0
	v_mfma_f32_16x16x32_bf16 v[2:5], v[168:171], v[164:167], 0
	v_mfma_f32_16x16x32_bf16 v[6:9], v[172:175], v[164:167], 0
	v_mfma_f32_16x16x32_bf16 v[10:13], v[180:183], v[164:167], 0
	v_mfma_f32_16x16x32_bf16 v[14:17], v[176:179], v[164:167], 0
	s_nop 0
	s_nop 0
	s_nop 0
	v_mfma_f32_16x16x32_bf16 v[62:65], v[216:219], v[184:187], v[62:65]
	v_mfma_f32_16x16x32_bf16 v[66:69], v[220:223], v[184:187], v[66:69]
	v_mfma_f32_16x16x32_bf16 v[70:73], v[224:227], v[184:187], v[70:73]
	v_mfma_f32_16x16x32_bf16 v[74:77], v[228:231], v[184:187], v[74:77]
	v_mfma_f32_16x16x32_bf16 v[54:57], v[216:219], v[204:207], v[54:57]
	v_mfma_f32_16x16x32_bf16 v[42:45], v[220:223], v[204:207], v[42:45]
	v_mfma_f32_16x16x32_bf16 v[46:49], v[224:227], v[204:207], v[46:49]
	v_mfma_f32_16x16x32_bf16 v[50:53], v[228:231], v[204:207], v[50:53]
	v_mfma_f32_16x16x32_bf16 v[38:41], v[216:219], v[208:211], v[38:41]
	v_mfma_f32_16x16x32_bf16 v[18:21], v[220:223], v[208:211], v[18:21]
	v_mfma_f32_16x16x32_bf16 v[22:25], v[224:227], v[208:211], v[22:25]
	v_mfma_f32_16x16x32_bf16 v[26:29], v[228:231], v[208:211], v[26:29]
	v_mfma_f32_16x16x32_bf16 v[2:5], v[216:219], v[212:215], v[2:5]
	v_mfma_f32_16x16x32_bf16 v[6:9], v[220:223], v[212:215], v[6:9]
	v_mfma_f32_16x16x32_bf16 v[10:13], v[224:227], v[212:215], v[10:13]
	v_mfma_f32_16x16x32_bf16 v[14:17], v[228:231], v[212:215], v[14:17]
	s_nop 0
	s_nop 0
	global_load_dwordx4 v[124:127], v[88:89], off offset:128
	global_load_dwordx4 v[148:151], v[90:91], off offset:128
	global_load_dwordx4 v[152:155], v[82:83], off offset:128
	global_load_dwordx4 v[164:167], v[94:95], off offset:128
	global_load_dwordx4 v[176:179], v[96:97], off offset:128
	global_load_dwordx4 v[180:183], v[92:93], off offset:128
	s_nop 0
	s_nop 0
	s_nop 0
	global_load_dwordx4 v[172:175], v[84:85], off offset:192
	global_load_dwordx4 v[168:171], v[86:87], off offset:192
	global_load_dwordx4 v[212:215], v[88:89], off offset:192
	s_nop 0
	global_load_dwordx4 v[208:211], v[90:91], off offset:192
	s_nop 0
	global_load_dwordx4 v[204:207], v[82:83], off offset:192
	s_waitcnt vmcnt(0)
; #define LAS __attribute__((address_space(3)))
; #define MFMA16(a, b, c) __builtin_amdgcn_mfma_f32_16x16x32_bf16((a), (b), (c), 0, 0, 0)
; template <int MT, int NT, class Epi>
; __device__ __forceinline__ void tail_splitk(LAS unsigned char* lds, const bf16_t* A, const bf16_t* Bt, int K, int row_base, int n_rt, int col_base, int n_ct, int it0, const Epi& E) {
;     ...
;         for (int ks = 0; ks < nks; ++ks) {
;             bf16x8 af[MT], bfv[NT];
; #pragma unroll
;             for (int mt = 0; mt < MT; ++mt) af[mt] = *(const bf16x8*)(ap + (size_t)mt * 16 * K + ks * 32);
; #pragma unroll
;             for (int nt = 0; nt < NT; ++nt) bfv[nt] = *(const bf16x8*)(bp + (size_t)nt * 16 * K + ks * 32);
; #pragma unroll
;             for (int mt = 0; mt < MT; ++mt)
; #pragma unroll
;                 for (int nt = 0; nt < NT; ++nt) acc[mt][nt] = MFMA16(bfv[nt], af[mt], acc[mt][nt]);
;         }
;         LAS float* pw = (LAS float*)(lds + w * WB);
; #pragma unroll
;         for (int mt = 0; mt < MT; ++mt)
; #pragma unroll
;             for (int nt = 0; nt < NT; ++nt) *(LAS f32x4*)(pw + (16 * mt + fr) * RS + 16 * nt + 4 * fq) = acc[mt][nt];
;         __syncthreads();
	s_nop 0
	s_nop 0
	s_nop 0
	v_mfma_f32_16x16x32_bf16 v[62:65], v[152:155], v[232:235], v[62:65]
	v_mfma_f32_16x16x32_bf16 v[66:69], v[164:167], v[232:235], v[66:69]
	v_mfma_f32_16x16x32_bf16 v[70:73], v[176:179], v[232:235], v[70:73]
	v_mfma_f32_16x16x32_bf16 v[30:33], v[180:183], v[232:235], v[74:77]
	v_mfma_f32_16x16x32_bf16 v[54:57], v[152:155], v[236:239], v[54:57]
	v_mfma_f32_16x16x32_bf16 v[42:45], v[164:167], v[236:239], v[42:45]
	v_mfma_f32_16x16x32_bf16 v[46:49], v[176:179], v[236:239], v[46:49]
	v_mfma_f32_16x16x32_bf16 v[34:37], v[180:183], v[236:239], v[50:53]
	v_mfma_f32_16x16x32_bf16 v[38:41], v[152:155], v[124:127], v[38:41]
	v_mfma_f32_16x16x32_bf16 v[18:21], v[164:167], v[124:127], v[18:21]
	v_mfma_f32_16x16x32_bf16 v[22:25], v[176:179], v[124:127], v[22:25]
	v_mfma_f32_16x16x32_bf16 v[26:29], v[180:183], v[124:127], v[26:29]
	v_mfma_f32_16x16x32_bf16 v[2:5], v[152:155], v[148:151], v[2:5]
	v_mfma_f32_16x16x32_bf16 v[6:9], v[164:167], v[148:151], v[6:9]
	v_mfma_f32_16x16x32_bf16 v[10:13], v[176:179], v[148:151], v[10:13]
	v_mfma_f32_16x16x32_bf16 v[14:17], v[180:183], v[148:151], v[14:17]
	s_nop 0
	s_nop 0
	s_nop 0
	global_load_dwordx4 v[184:187], v[94:95], off offset:192
	s_nop 0
	global_load_dwordx4 v[216:219], v[96:97], off offset:192
	s_nop 0
	global_load_dwordx4 v[220:223], v[92:93], off offset:192
	s_nop 0
	s_nop 0
	s_nop 0
	s_waitcnt vmcnt(0)
	s_nop 0
	s_nop 0
	s_nop 0
	v_mfma_f32_16x16x32_bf16 v[62:65], v[204:207], v[172:175], v[62:65]
	v_mfma_f32_16x16x32_bf16 v[66:69], v[184:187], v[172:175], v[66:69]
	v_mfma_f32_16x16x32_bf16 v[70:73], v[216:219], v[172:175], v[70:73]
	v_mfma_f32_16x16x32_bf16 v[30:33], v[220:223], v[172:175], v[30:33]
	v_mfma_f32_16x16x32_bf16 v[50:53], v[204:207], v[168:171], v[54:57]
	v_mfma_f32_16x16x32_bf16 v[42:45], v[184:187], v[168:171], v[42:45]
	v_mfma_f32_16x16x32_bf16 v[46:49], v[216:219], v[168:171], v[46:49]
	v_mfma_f32_16x16x32_bf16 v[34:37], v[220:223], v[168:171], v[34:37]
	v_mfma_f32_16x16x32_bf16 v[38:41], v[204:207], v[212:215], v[38:41]
	v_mfma_f32_16x16x32_bf16 v[18:21], v[184:187], v[212:215], v[18:21]
	v_mfma_f32_16x16x32_bf16 v[22:25], v[216:219], v[212:215], v[22:25]
	v_mfma_f32_16x16x32_bf16 v[26:29], v[220:223], v[212:215], v[26:29]
	v_mfma_f32_16x16x32_bf16 v[2:5], v[204:207], v[208:211], v[2:5]
	v_mfma_f32_16x16x32_bf16 v[6:9], v[184:187], v[208:211], v[6:9]
	v_mfma_f32_16x16x32_bf16 v[10:13], v[216:219], v[208:211], v[10:13]
	v_mfma_f32_16x16x32_bf16 v[14:17], v[220:223], v[208:211], v[14:17]
	ds_write_b128 v102, v[62:65]
	ds_write_b128 v102, v[66:69] offset:64
	ds_write_b128 v102, v[70:73] offset:128
	ds_write_b128 v102, v[30:33] offset:192
	ds_write_b128 v102, v[50:53] offset:4352
	ds_write_b128 v102, v[42:45] offset:4416
	ds_write_b128 v102, v[46:49] offset:4480
	ds_write_b128 v102, v[34:37] offset:4544
	ds_write_b128 v102, v[38:41] offset:8704
	ds_write_b128 v102, v[18:21] offset:8768
	ds_write_b128 v102, v[22:25] offset:8832
	ds_write_b128 v102, v[26:29] offset:8896
	ds_write_b128 v102, v[2:5] offset:13056
	ds_write_b128 v102, v[6:9] offset:13120
	ds_write_b128 v102, v[10:13] offset:13184
	ds_write_b128 v102, v[14:17] offset:13248
	s_waitcnt lgkmcnt(0)
	s_barrier
	s_and_saveexec_b64 s[4:5], vcc
	s_cbranch_execz .LBB0_991
	v_add_u32_e32 v0, s38, v101
	s_mov_b64 s[38:39], 0
	v_mov_b32_e32 v2, v100
	v_mov_b32_e32 v3, v98

; #define LAS __attribute__((address_space(3)))
; #define MFMA16(a, b, c) __builtin_amdgcn_mfma_f32_16x16x32_bf16((a), (b), (c), 0, 0, 0)
;     template <int QPR> __device__ __forceinline__ void tailq(int row, int c, const f32x4 v, int) const { quad(row, c, v); }
;     template <int QPR> __device__ __forceinline__ void tailq(int row, int c, const f32x4 v, int) const { quad(row, c, v); }
; template <int MT, int NT, class Epi>
; __device__ __forceinline__ void tail_splitk(LAS unsigned char* lds, const bf16_t* A, const bf16_t* Bt, int K, int row_base, int n_rt, int col_base, int n_ct, int it0, const Epi& E) {
;     ...
;         const bf16_t* ap = A + (size_t)(r0 + fr) * K + fq * 8 + w * nks * 32; const bf16_t* bp = Bt + (size_t)(c0 + fr) * K + fq * 8 + w * nks * 32;
; #pragma unroll 4
;         for (int ks = 0; ks < nks; ++ks) {
;             bf16x8 af[MT], bfv[NT];
; #pragma unroll
;             for (int mt = 0; mt < MT; ++mt) af[mt] = *(const bf16x8*)(ap + (size_t)mt * 16 * K + ks * 32);
; #pragma unroll
;             for (int nt = 0; nt < NT; ++nt) bfv[nt] = *(const bf16x8*)(bp + (size_t)nt * 16 * K + ks * 32);
; #pragma unroll
;             for (int mt = 0; mt < MT; ++mt)
; #pragma unroll
;                 for (int nt = 0; nt < NT; ++nt) acc[mt][nt] = MFMA16(bfv[nt], af[mt], acc[mt][nt]);
;         }
;         LAS float* pw = (LAS float*)(lds + w * WB);
; #pragma unroll
;         for (int mt = 0; mt < MT; ++mt)
; #pragma unroll
;             for (int nt = 0; nt < NT; ++nt) *(LAS f32x4*)(pw + (16 * mt + fr) * RS + 16 * nt + 4 * fq) = acc[mt][nt];
;         __syncthreads();
; #pragma unroll
;         for (int q = tid; q < MT * 16 * QPR; q += 512) { const int row = q / QPR, qc = q % QPR;
;             f32x4 v = {0.f, 0.f, 0.f, 0.f};
; #pragma unroll
;             for (int ww = 0; ww < 8; ++ww) v = v + *(const LAS f32x4*)(lds + ww * WB + (row * RS + qc * 4) * 4);
;             E.template tailq<QPR>(r0 + row, c0 + qc * 4, v, c0); }
.LBB0_1169:
	v_lshl_add_u64 v[42:43], v[38:39], 0, s[38:39]
	s_mov_b32 s0, 0x1e820000
	v_add_co_u32_e64 v46, s[0:1], s0, v42
	v_lshl_add_u64 v[78:79], v[40:41], 0, s[38:39]
	s_nop 0
	v_addc_co_u32_e64 v47, s[0:1], 0, v43, s[0:1]
	s_mov_b32 s0, 0x1e838000
	s_nop 0
	v_add_co_u32_e64 v50, s[0:1], s0, v42
	global_load_dwordx4 v[84:87], v[46:47], off
	s_nop 0
	v_addc_co_u32_e64 v51, s[0:1], 0, v43, s[0:1]
	s_mov_b32 s0, 0x8200000
	s_nop 0
	v_add_co_u32_e64 v42, s[0:1], s0, v78
	global_load_dwordx4 v[88:91], v[50:51], off
	s_nop 0
	v_addc_co_u32_e64 v43, s[0:1], 0, v79, s[0:1]
	s_mov_b32 s0, 0x8218000
	s_nop 0
	v_add_co_u32_e64 v44, s[0:1], s0, v78
	global_load_dwordx4 v[92:95], v[42:43], off
	s_nop 0
	v_addc_co_u32_e64 v45, s[0:1], 0, v79, s[0:1]
	s_mov_b32 s0, 0x8230000
	s_nop 0
	v_add_co_u32_e64 v48, s[0:1], s0, v78
	global_load_dwordx4 v[96:99], v[44:45], off
	s_nop 0
	v_addc_co_u32_e64 v49, s[0:1], 0, v79, s[0:1]
	s_mov_b32 s0, 0x8248000
	s_nop 0
	v_add_co_u32_e64 v82, s[0:1], s0, v78
	global_load_dwordx4 v[100:103], v[48:49], off
	s_nop 0
	v_addc_co_u32_e64 v83, s[0:1], 0, v79, s[0:1]
	global_load_dwordx4 v[104:107], v[82:83], off
	s_add_u32 s38, s38, 0x100
	s_addc_u32 s39, s39, 0
	s_cmpk_lg_i32 s38, 0x300
	s_nop 0
	s_nop 0
	s_nop 0
	global_load_dwordx4 v[108:111], v[46:47], off offset:64
	global_load_dwordx4 v[112:115], v[50:51], off offset:64
	global_load_dwordx4 v[116:119], v[42:43], off offset:64
	global_load_dwordx4 v[120:123], v[44:45], off offset:64
	global_load_dwordx4 v[124:127], v[48:49], off offset:64
	global_load_dwordx4 v[148:151], v[82:83], off offset:64
	s_nop 0
	s_nop 0
	s_nop 0
	global_load_dwordx4 v[152:155], v[46:47], off offset:128
	global_load_dwordx4 v[164:167], v[50:51], off offset:128
	global_load_dwordx4 v[168:171], v[42:43], off offset:128
	global_load_dwordx4 v[172:175], v[44:45], off offset:128
	global_load_dwordx4 v[176:179], v[48:49], off offset:128
	global_load_dwordx4 v[180:183], v[82:83], off offset:128
	s_nop 0
	s_nop 0
	s_nop 0
	global_load_dwordx4 v[184:187], v[46:47], off offset:192
	global_load_dwordx4 v[204:207], v[50:51], off offset:192
	global_load_dwordx4 v[208:211], v[42:43], off offset:192
	s_nop 0
	global_load_dwordx4 v[212:215], v[44:45], off offset:192
	s_nop 0
	global_load_dwordx4 v[216:219], v[48:49], off offset:192
	s_nop 0
	global_load_dwordx4 v[220:223], v[82:83], off offset:192
	s_nop 0
	s_nop 0
	s_nop 0
	s_waitcnt vmcnt(0)
	s_nop 0
	s_nop 0
	s_nop 0
	v_mfma_f32_16x16x32_bf16 v[30:33], v[92:95], v[84:87], v[30:33]
	v_mfma_f32_16x16x32_bf16 v[26:29], v[96:99], v[84:87], v[26:29]
	v_mfma_f32_16x16x32_bf16 v[22:25], v[100:103], v[84:87], v[22:25]
	v_mfma_f32_16x16x32_bf16 v[18:21], v[104:107], v[84:87], v[18:21]
	v_mfma_f32_16x16x32_bf16 v[14:17], v[92:95], v[88:91], v[14:17]
	v_mfma_f32_16x16x32_bf16 v[10:13], v[96:99], v[88:91], v[10:13]
	v_mfma_f32_16x16x32_bf16 v[6:9], v[100:103], v[88:91], v[6:9]
	v_mfma_f32_16x16x32_bf16 v[2:5], v[104:107], v[88:91], v[2:5]
	s_nop 0
	s_nop 0
	s_nop 0
	v_mfma_f32_16x16x32_bf16 v[30:33], v[116:119], v[108:111], v[30:33]
	v_mfma_f32_16x16x32_bf16 v[26:29], v[120:123], v[108:111], v[26:29]
	v_mfma_f32_16x16x32_bf16 v[22:25], v[124:127], v[108:111], v[22:25]
	v_mfma_f32_16x16x32_bf16 v[18:21], v[148:151], v[108:111], v[18:21]
	v_mfma_f32_16x16x32_bf16 v[14:17], v[116:119], v[112:115], v[14:17]
	v_mfma_f32_16x16x32_bf16 v[10:13], v[120:123], v[112:115], v[10:13]
	v_mfma_f32_16x16x32_bf16 v[6:9], v[124:127], v[112:115], v[6:9]
	v_mfma_f32_16x16x32_bf16 v[2:5], v[148:151], v[112:115], v[2:5]
	s_nop 0
	s_nop 0
	s_nop 0
	v_mfma_f32_16x16x32_bf16 v[30:33], v[168:171], v[152:155], v[30:33]
	v_mfma_f32_16x16x32_bf16 v[26:29], v[172:175], v[152:155], v[26:29]
	v_mfma_f32_16x16x32_bf16 v[22:25], v[176:179], v[152:155], v[22:25]
	v_mfma_f32_16x16x32_bf16 v[18:21], v[180:183], v[152:155], v[18:21]
	v_mfma_f32_16x16x32_bf16 v[14:17], v[168:171], v[164:167], v[14:17]
	v_mfma_f32_16x16x32_bf16 v[10:13], v[172:175], v[164:167], v[10:13]
	v_mfma_f32_16x16x32_bf16 v[6:9], v[176:179], v[164:167], v[6:9]
	v_mfma_f32_16x16x32_bf16 v[2:5], v[180:183], v[164:167], v[2:5]
	s_nop 0
	s_nop 0
	s_nop 0
	v_mfma_f32_16x16x32_bf16 v[30:33], v[208:211], v[184:187], v[30:33]
	v_mfma_f32_16x16x32_bf16 v[26:29], v[212:215], v[184:187], v[26:29]
	v_mfma_f32_16x16x32_bf16 v[22:25], v[216:219], v[184:187], v[22:25]
	v_mfma_f32_16x16x32_bf16 v[18:21], v[220:223], v[184:187], v[18:21]
	v_mfma_f32_16x16x32_bf16 v[14:17], v[208:211], v[204:207], v[14:17]
	v_mfma_f32_16x16x32_bf16 v[10:13], v[212:215], v[204:207], v[10:13]
	v_mfma_f32_16x16x32_bf16 v[6:9], v[216:219], v[204:207], v[6:9]
	v_mfma_f32_16x16x32_bf16 v[2:5], v[220:223], v[204:207], v[2:5]
	s_cbranch_scc1 .LBB0_1169
	ds_write_b128 v56, v[30:33]
	ds_write_b128 v56, v[26:29] offset:64
	ds_write_b128 v56, v[22:25] offset:128
	ds_write_b128 v56, v[18:21] offset:192
	ds_write_b128 v56, v[14:17] offset:4352
	ds_write_b128 v56, v[10:13] offset:4416
	ds_write_b128 v56, v[6:9] offset:4480
	ds_write_b128 v56, v[2:5] offset:4544
	s_waitcnt lgkmcnt(0)
	s_barrier
	s_and_saveexec_b64 s[38:39], vcc
	s_cbranch_execz .LBB0_1167
	s_lshl_b32 s0, s4, 3
	v_and_b32_e32 v2, 64, v203
	s_sub_i32 s0, s30, s0
	v_add_u32_e32 v2, 64, v2
	v_xor_b32_e32 v3, 1, v203
	s_lshl_b32 s52, s0, 5
	v_cmp_lt_i32_e64 s[0:1], v3, v2
	s_ashr_i32 s5, s4, 31
	s_addk_i32 s52, 0x4000
	v_cndmask_b32_e64 v3, v203, v3, s[0:1]
	v_lshlrev_b32_e32 v4, 2, v3
	v_xor_b32_e32 v3, 2, v203
	v_cmp_lt_i32_e64 s[0:1], v3, v2
	v_add_u32_e32 v8, s40, v54
	s_mov_b64 s[40:41], 0
	v_cndmask_b32_e64 v3, v203, v3, s[0:1]
	v_lshlrev_b32_e32 v5, 2, v3
	v_xor_b32_e32 v3, 4, v203
	v_cmp_lt_i32_e64 s[0:1], v3, v2
	v_mov_b32_e32 v9, v55
	v_mov_b32_e32 v10, v0
	v_cndmask_b32_e64 v3, v203, v3, s[0:1]
	v_lshlrev_b32_e32 v6, 2, v3
	v_xor_b32_e32 v3, 8, v203
	v_cmp_lt_i32_e64 s[0:1], v3, v2
	s_nop 1
	v_cndmask_b32_e64 v2, v203, v3, s[0:1]
	s_lshl_b64 s[0:1], s[4:5], 2
	s_add_u32 s4, s14, s0
	v_lshlrev_b32_e32 v7, 2, v2
	s_addc_u32 s5, s15, s1
	s_branch .LBB0_1173

; __global__ void __launch_bounds__(512, 2) mega(Params KP) {
	.amdhsa_kernel _Z4mega6Params
		.amdhsa_group_segment_fixed_size 0
		.amdhsa_private_segment_fixed_size 0
		.amdhsa_kernarg_size 504
		.amdhsa_user_sgpr_count 2
		.amdhsa_user_sgpr_dispatch_ptr 0
		.amdhsa_user_sgpr_queue_ptr 0
		.amdhsa_user_sgpr_kernarg_segment_ptr 1
		.amdhsa_user_sgpr_dispatch_id 0
		.amdhsa_user_sgpr_kernarg_preload_length 0
		.amdhsa_user_sgpr_kernarg_preload_offset 0
		.amdhsa_user_sgpr_private_segment_size 0
		.amdhsa_uses_dynamic_stack 0
		.amdhsa_enable_private_segment 0
		.amdhsa_system_sgpr_workgroup_id_x 1
		.amdhsa_system_sgpr_workgroup_id_y 0
		.amdhsa_system_sgpr_workgroup_id_z 0
		.amdhsa_system_sgpr_workgroup_info 0
		.amdhsa_system_vgpr_workitem_id 2
		.amdhsa_next_free_vgpr 252
		.amdhsa_next_free_sgpr 102
		.amdhsa_accum_offset 252
		.amdhsa_reserve_vcc 1
		.amdhsa_float_round_mode_32 0
		.amdhsa_float_round_mode_16_64 0
		.amdhsa_float_denorm_mode_32 3
		.amdhsa_float_denorm_mode_16_64 3
		.amdhsa_dx10_clamp 1
		.amdhsa_ieee_mode 1
		.amdhsa_fp16_overflow 0
		.amdhsa_tg_split 0
		.amdhsa_exception_fp_ieee_invalid_op 0
		.amdhsa_exception_fp_denorm_src 0
		.amdhsa_exception_fp_ieee_div_zero 0
		.amdhsa_exception_fp_ieee_overflow 0
		.amdhsa_exception_fp_ieee_underflow 0
		.amdhsa_exception_fp_ieee_inexact 0
		.amdhsa_exception_int_div_zero 0
	.end_amdhsa_kernel

; #define LAS __attribute__((address_space(3)))
; __global__ void __launch_bounds__(512, 2) mega(Params KP) {
;     extern __shared__ __attribute__((aligned(16))) unsigned char lds_raw[];
;     LAS unsigned char* lds = (LAS unsigned char*)lds_raw;
amdhsa.kernels:
  - .agpr_count:     0
    .args:
      - .offset:         0
        .size:           248
        .value_kind:     by_value
      - .offset:         248
        .size:           4
        .value_kind:     hidden_block_count_x
      - .offset:         252
        .size:           4
        .value_kind:     hidden_block_count_y
      - .offset:         256
        .size:           4
        .value_kind:     hidden_block_count_z
      - .offset:         260
        .size:           2
        .value_kind:     hidden_group_size_x
      - .offset:         262
        .size:           2
        .value_kind:     hidden_group_size_y
      - .offset:         264
        .size:           2
        .value_kind:     hidden_group_size_z
      - .offset:         266
        .size:           2
        .value_kind:     hidden_remainder_x
      - .offset:         268
        .size:           2
        .value_kind:     hidden_remainder_y
      - .offset:         270
        .size:           2
        .value_kind:     hidden_remainder_z
      - .offset:         288
        .size:           8
        .value_kind:     hidden_global_offset_x
      - .offset:         296
        .size:           8
        .value_kind:     hidden_global_offset_y
      - .offset:         304
        .size:           8
        .value_kind:     hidden_global_offset_z
      - .offset:         312
        .size:           2
        .value_kind:     hidden_grid_dims
      - .offset:         336
        .size:           8
        .value_kind:     hidden_multigrid_sync_arg
      - .offset:         368
        .size:           4
        .value_kind:     hidden_dynamic_lds_size
    .group_segment_fixed_size: 0
    .kernarg_segment_align: 8
    .kernarg_segment_size: 504
    .language:       OpenCL C
    .language_version:
      - 2
      - 0
    .max_flat_workgroup_size: 512
    .name:           _Z4mega6Params
    .private_segment_fixed_size: 0
    .sgpr_count:     108
    .sgpr_spill_count: 234
    .symbol:         _Z4mega6Params.kd
    .uniform_work_group_size: 1
    .uses_dynamic_stack: false
    .vgpr_count:     252
    .vgpr_spill_count: 0
    .wavefront_size: 64
